# GEMM unit starts: the redundant first 128-register accumulator zero-fill (immediately overwritten by the loop-entry zero-fill) now runs only on the never-taken empty-K path, in all 18 GEMM copies; on
# speedup vs baseline: 1.0074x; 1.0074x over previous
; template <class Epi, class Sched, bool ALIGN_EPI = false, bool SP2 = false>
; __device__ __forceinline__ void gemm_phase(PG8_LAS unsigned char* lds, const Gemm g, const Sched& S, const Epi& E) {
;     ...
;         const bool has_next = S.next(ui + 1, nxt);
;         const char* nA = has_next ? (const char*)g.A + (size_t)nxt.pm * tstep : cA; const char* nB = has_next ? (const char*)g.Bt + (size_t)nxt.pn * tstep : cB;
;         for (int t = 0; t < nt; t += 2) {
;             const bool last = (t == nt - 2);
;             const char* a1 = cA + (size_t)(t + 1) * kstep;
;             const char* a2 = last ? nA : cA + (size_t)(t + 2) * kstep; const char* b2 = last ? nB : cB + (size_t)(t + 2) * kstep;
;             const char* a3 = a2 + kstep; const char* b3 = b2 + kstep;
;     ...
; #pragma unroll
;         for (int a = 0; a < 2; ++a)
; #pragma unroll
;             for (int b = 0; b < 2; ++b)
; #pragma unroll
;                 for (int m = 0; m < 4; ++m)
; #pragma unroll
;                     for (int n = 0; n < 2; ++n) acc[a][b][m][n] = (f32x4){0.f, 0.f, 0.f, 0.f};
;         cur = nxt; cA = nA; cB = nB; ++ui;
.LBB0_302:
	s_and_b64 vcc, exec, s[6:7]
	s_cbranch_vccz .Lzs_17
	v_mov_b32_e32 v127, 0
	v_mov_b32_e32 v126, v127
	v_mov_b32_e32 v125, v127
	v_mov_b32_e32 v124, v127
	v_mov_b32_e32 v119, v127
	v_mov_b32_e32 v118, v127
	v_mov_b32_e32 v117, v127
	v_mov_b32_e32 v116, v127
	v_mov_b32_e32 v111, v127
	v_mov_b32_e32 v110, v127
	v_mov_b32_e32 v109, v127
	v_mov_b32_e32 v108, v127
	v_mov_b32_e32 v103, v127
	v_mov_b32_e32 v102, v127
	v_mov_b32_e32 v101, v127
	v_mov_b32_e32 v100, v127
	v_mov_b32_e32 v95, v127
	v_mov_b32_e32 v94, v127
	v_mov_b32_e32 v93, v127
	v_mov_b32_e32 v92, v127
	v_mov_b32_e32 v87, v127
	v_mov_b32_e32 v86, v127
	v_mov_b32_e32 v85, v127
	v_mov_b32_e32 v84, v127
	v_mov_b32_e32 v79, v127
	v_mov_b32_e32 v78, v127
	v_mov_b32_e32 v77, v127
	v_mov_b32_e32 v76, v127
	v_mov_b32_e32 v71, v127
	v_mov_b32_e32 v70, v127
	v_mov_b32_e32 v69, v127
	v_mov_b32_e32 v68, v127
	v_mov_b32_e32 v123, v127
	v_mov_b32_e32 v122, v127
	v_mov_b32_e32 v121, v127
	v_mov_b32_e32 v120, v127
	v_mov_b32_e32 v115, v127
	v_mov_b32_e32 v114, v127
	v_mov_b32_e32 v113, v127
	v_mov_b32_e32 v112, v127
	v_mov_b32_e32 v107, v127
	v_mov_b32_e32 v106, v127
	v_mov_b32_e32 v105, v127
	v_mov_b32_e32 v104, v127
	v_mov_b32_e32 v99, v127
	v_mov_b32_e32 v98, v127
	v_mov_b32_e32 v97, v127
	v_mov_b32_e32 v96, v127
	v_mov_b32_e32 v91, v127
	v_mov_b32_e32 v90, v127
	v_mov_b32_e32 v89, v127
	v_mov_b32_e32 v88, v127
	v_mov_b32_e32 v83, v127
	v_mov_b32_e32 v82, v127
	v_mov_b32_e32 v81, v127
	v_mov_b32_e32 v80, v127
	v_mov_b32_e32 v75, v127
	v_mov_b32_e32 v74, v127
	v_mov_b32_e32 v73, v127
	v_mov_b32_e32 v72, v127
	v_mov_b32_e32 v67, v127
	v_mov_b32_e32 v66, v127
	v_mov_b32_e32 v65, v127
	v_mov_b32_e32 v64, v127
	v_mov_b32_e32 v63, v127
	v_mov_b32_e32 v62, v127
	v_mov_b32_e32 v61, v127
	v_mov_b32_e32 v60, v127
	v_mov_b32_e32 v55, v127
	v_mov_b32_e32 v54, v127
	v_mov_b32_e32 v53, v127
	v_mov_b32_e32 v52, v127
	v_mov_b32_e32 v47, v127
	v_mov_b32_e32 v46, v127
	v_mov_b32_e32 v45, v127
	v_mov_b32_e32 v44, v127
	v_mov_b32_e32 v39, v127
	v_mov_b32_e32 v38, v127
	v_mov_b32_e32 v37, v127
	v_mov_b32_e32 v36, v127
	v_mov_b32_e32 v31, v127
	v_mov_b32_e32 v30, v127
	v_mov_b32_e32 v29, v127
	v_mov_b32_e32 v28, v127
	v_mov_b32_e32 v23, v127
	v_mov_b32_e32 v22, v127
	v_mov_b32_e32 v21, v127
	v_mov_b32_e32 v20, v127
	v_mov_b32_e32 v15, v127
	v_mov_b32_e32 v14, v127
	v_mov_b32_e32 v13, v127
	v_mov_b32_e32 v12, v127
	v_mov_b32_e32 v7, v127
	v_mov_b32_e32 v6, v127
	v_mov_b32_e32 v5, v127
	v_mov_b32_e32 v4, v127
	v_mov_b32_e32 v59, v127
	v_mov_b32_e32 v58, v127
	v_mov_b32_e32 v57, v127
	v_mov_b32_e32 v56, v127
	v_mov_b32_e32 v51, v127
	v_mov_b32_e32 v50, v127
	v_mov_b32_e32 v49, v127
	v_mov_b32_e32 v48, v127
	v_mov_b32_e32 v43, v127
	v_mov_b32_e32 v42, v127
	v_mov_b32_e32 v41, v127
	v_mov_b32_e32 v40, v127
	v_mov_b32_e32 v35, v127
	v_mov_b32_e32 v34, v127
	v_mov_b32_e32 v33, v127
	v_mov_b32_e32 v32, v127
	v_mov_b32_e32 v27, v127
	v_mov_b32_e32 v26, v127
	v_mov_b32_e32 v25, v127
	v_mov_b32_e32 v24, v127
	v_mov_b32_e32 v19, v127
	v_mov_b32_e32 v18, v127
	v_mov_b32_e32 v17, v127
	v_mov_b32_e32 v16, v127
	v_mov_b32_e32 v11, v127
	v_mov_b32_e32 v10, v127
	v_mov_b32_e32 v9, v127
	v_mov_b32_e32 v8, v127
	v_mov_b32_e32 v3, v127
	v_mov_b32_e32 v2, v127
	v_mov_b32_e32 v1, v127
	v_mov_b32_e32 v0, v127
	s_branch .LBB0_305
.Lzs_17:
	v_mov_b32_e32 v0, 0
	v_lshl_add_u64 v[158:159], v[158:159], 0, s[26:27]
	v_lshl_add_u64 v[160:161], v[160:161], 0, s[22:23]
	s_mov_b32 s10, 0
	v_mov_b32_e32 v1, v0
	v_mov_b32_e32 v2, v0
	v_mov_b32_e32 v3, v0
	v_mov_b32_e32 v8, v0
	v_mov_b32_e32 v9, v0
	v_mov_b32_e32 v10, v0
	v_mov_b32_e32 v11, v0
	v_mov_b32_e32 v16, v0
	v_mov_b32_e32 v17, v0
	v_mov_b32_e32 v18, v0
	v_mov_b32_e32 v19, v0
	v_mov_b32_e32 v24, v0
	v_mov_b32_e32 v25, v0
	v_mov_b32_e32 v26, v0
	v_mov_b32_e32 v27, v0
	v_mov_b32_e32 v32, v0
	v_mov_b32_e32 v33, v0
	v_mov_b32_e32 v34, v0
	v_mov_b32_e32 v35, v0
	v_mov_b32_e32 v40, v0
	v_mov_b32_e32 v41, v0
	v_mov_b32_e32 v42, v0
	v_mov_b32_e32 v43, v0
	v_mov_b32_e32 v48, v0
	v_mov_b32_e32 v49, v0
	v_mov_b32_e32 v50, v0
	v_mov_b32_e32 v51, v0
	v_mov_b32_e32 v56, v0
	v_mov_b32_e32 v57, v0
	v_mov_b32_e32 v58, v0
	v_mov_b32_e32 v59, v0
	v_mov_b32_e32 v4, v0
	v_mov_b32_e32 v5, v0
	v_mov_b32_e32 v6, v0
	v_mov_b32_e32 v7, v0
	v_mov_b32_e32 v12, v0
	v_mov_b32_e32 v13, v0
	v_mov_b32_e32 v14, v0
	v_mov_b32_e32 v15, v0
	v_mov_b32_e32 v20, v0
	v_mov_b32_e32 v21, v0
	v_mov_b32_e32 v22, v0
	v_mov_b32_e32 v23, v0
	v_mov_b32_e32 v28, v0
	v_mov_b32_e32 v29, v0
	v_mov_b32_e32 v30, v0
	v_mov_b32_e32 v31, v0
	v_mov_b32_e32 v36, v0
	v_mov_b32_e32 v37, v0
	v_mov_b32_e32 v38, v0
	v_mov_b32_e32 v39, v0
	v_mov_b32_e32 v44, v0
	v_mov_b32_e32 v45, v0
	v_mov_b32_e32 v46, v0
	v_mov_b32_e32 v47, v0
	v_mov_b32_e32 v52, v0
	v_mov_b32_e32 v53, v0
	v_mov_b32_e32 v54, v0
	v_mov_b32_e32 v55, v0
	v_mov_b32_e32 v60, v0
	v_mov_b32_e32 v61, v0
	v_mov_b32_e32 v62, v0
	v_mov_b32_e32 v63, v0
	v_mov_b32_e32 v64, v0
	v_mov_b32_e32 v65, v0
	v_mov_b32_e32 v66, v0
	v_mov_b32_e32 v67, v0
	v_mov_b32_e32 v72, v0
	v_mov_b32_e32 v73, v0
	v_mov_b32_e32 v74, v0
	v_mov_b32_e32 v75, v0
	v_mov_b32_e32 v80, v0
	v_mov_b32_e32 v81, v0
	v_mov_b32_e32 v82, v0
	v_mov_b32_e32 v83, v0
	v_mov_b32_e32 v88, v0
	v_mov_b32_e32 v89, v0
	v_mov_b32_e32 v90, v0
	v_mov_b32_e32 v91, v0
	v_mov_b32_e32 v96, v0
	v_mov_b32_e32 v97, v0
	v_mov_b32_e32 v98, v0
	v_mov_b32_e32 v99, v0
	v_mov_b32_e32 v104, v0
	v_mov_b32_e32 v105, v0
	v_mov_b32_e32 v106, v0
	v_mov_b32_e32 v107, v0
	v_mov_b32_e32 v112, v0
	v_mov_b32_e32 v113, v0
	v_mov_b32_e32 v114, v0
	v_mov_b32_e32 v115, v0
	v_mov_b32_e32 v120, v0
	v_mov_b32_e32 v121, v0
	v_mov_b32_e32 v122, v0
	v_mov_b32_e32 v123, v0
	v_mov_b32_e32 v68, v0
	v_mov_b32_e32 v69, v0
	v_mov_b32_e32 v70, v0
	v_mov_b32_e32 v71, v0
	v_mov_b32_e32 v76, v0
	v_mov_b32_e32 v77, v0
	v_mov_b32_e32 v78, v0
	v_mov_b32_e32 v79, v0
	v_mov_b32_e32 v84, v0
	v_mov_b32_e32 v85, v0
	v_mov_b32_e32 v86, v0
	v_mov_b32_e32 v87, v0
	v_mov_b32_e32 v92, v0
	v_mov_b32_e32 v93, v0
	v_mov_b32_e32 v94, v0
	v_mov_b32_e32 v95, v0
	v_mov_b32_e32 v100, v0
	v_mov_b32_e32 v101, v0
	v_mov_b32_e32 v102, v0
	v_mov_b32_e32 v103, v0
	v_mov_b32_e32 v108, v0
	v_mov_b32_e32 v109, v0
	v_mov_b32_e32 v110, v0
	v_mov_b32_e32 v111, v0
	v_mov_b32_e32 v116, v0
	v_mov_b32_e32 v117, v0
	v_mov_b32_e32 v118, v0
	v_mov_b32_e32 v119, v0
	v_mov_b32_e32 v124, v0
	v_mov_b32_e32 v125, v0
	v_mov_b32_e32 v126, v0
	v_mov_b32_e32 v127, v0
	.p2align	6

; template <class Epi, class Sched, bool ALIGN_EPI = false, bool SP2 = false>
; __device__ __forceinline__ void gemm_phase(PG8_LAS unsigned char* lds, const Gemm g, const Sched& S, const Epi& E) {
;     ...
;         const bool has_next = S.next(ui + 1, nxt);
;         const char* nA = has_next ? (const char*)g.A + (size_t)nxt.pm * tstep : cA; const char* nB = has_next ? (const char*)g.Bt + (size_t)nxt.pn * tstep : cB;
;         for (int t = 0; t < nt; t += 2) {
;             const bool last = (t == nt - 2);
;             const char* a1 = cA + (size_t)(t + 1) * kstep;
;             const char* a2 = last ? nA : cA + (size_t)(t + 2) * kstep; const char* b2 = last ? nB : cB + (size_t)(t + 2) * kstep;
;             const char* a3 = a2 + kstep; const char* b3 = b2 + kstep;
;     ...
; #pragma unroll
;         for (int a = 0; a < 2; ++a)
; #pragma unroll
;             for (int b = 0; b < 2; ++b)
; #pragma unroll
;                 for (int m = 0; m < 4; ++m)
; #pragma unroll
;                     for (int n = 0; n < 2; ++n) acc[a][b][m][n] = (f32x4){0.f, 0.f, 0.f, 0.f};
;         cur = nxt; cA = nA; cB = nB; ++ui;
.LBB0_369:
	s_and_b64 vcc, exec, s[8:9]
	s_waitcnt lgkmcnt(0)
	s_cbranch_vccz .Lzs_16
	v_mov_b32_e32 v127, 0
	v_mov_b32_e32 v126, v127
	v_mov_b32_e32 v125, v127
	v_mov_b32_e32 v124, v127
	v_mov_b32_e32 v131, v127
	v_mov_b32_e32 v130, v127
	v_mov_b32_e32 v129, v127
	v_mov_b32_e32 v128, v127
	v_mov_b32_e32 v115, v127
	v_mov_b32_e32 v114, v127
	v_mov_b32_e32 v113, v127
	v_mov_b32_e32 v112, v127
	v_mov_b32_e32 v111, v127
	v_mov_b32_e32 v110, v127
	v_mov_b32_e32 v109, v127
	v_mov_b32_e32 v108, v127
	v_mov_b32_e32 v99, v127
	v_mov_b32_e32 v98, v127
	v_mov_b32_e32 v97, v127
	v_mov_b32_e32 v96, v127
	v_mov_b32_e32 v95, v127
	v_mov_b32_e32 v94, v127
	v_mov_b32_e32 v93, v127
	v_mov_b32_e32 v92, v127
	v_mov_b32_e32 v83, v127
	v_mov_b32_e32 v82, v127
	v_mov_b32_e32 v81, v127
	v_mov_b32_e32 v80, v127
	v_mov_b32_e32 v79, v127
	v_mov_b32_e32 v78, v127
	v_mov_b32_e32 v77, v127
	v_mov_b32_e32 v76, v127
	v_mov_b32_e32 v123, v127
	v_mov_b32_e32 v122, v127
	v_mov_b32_e32 v121, v127
	v_mov_b32_e32 v120, v127
	v_mov_b32_e32 v119, v127
	v_mov_b32_e32 v118, v127
	v_mov_b32_e32 v117, v127
	v_mov_b32_e32 v116, v127
	v_mov_b32_e32 v107, v127
	v_mov_b32_e32 v106, v127
	v_mov_b32_e32 v105, v127
	v_mov_b32_e32 v104, v127
	v_mov_b32_e32 v103, v127
	v_mov_b32_e32 v102, v127
	v_mov_b32_e32 v101, v127
	v_mov_b32_e32 v100, v127
	v_mov_b32_e32 v91, v127
	v_mov_b32_e32 v90, v127
	v_mov_b32_e32 v89, v127
	v_mov_b32_e32 v88, v127
	v_mov_b32_e32 v87, v127
	v_mov_b32_e32 v86, v127
	v_mov_b32_e32 v85, v127
	v_mov_b32_e32 v84, v127
	v_mov_b32_e32 v75, v127
	v_mov_b32_e32 v74, v127
	v_mov_b32_e32 v73, v127
	v_mov_b32_e32 v72, v127
	v_mov_b32_e32 v71, v127
	v_mov_b32_e32 v70, v127
	v_mov_b32_e32 v69, v127
	v_mov_b32_e32 v68, v127
	v_mov_b32_e32 v67, v127
	v_mov_b32_e32 v66, v127
	v_mov_b32_e32 v65, v127
	v_mov_b32_e32 v64, v127
	v_mov_b32_e32 v63, v127
	v_mov_b32_e32 v62, v127
	v_mov_b32_e32 v61, v127
	v_mov_b32_e32 v60, v127
	v_mov_b32_e32 v51, v127
	v_mov_b32_e32 v50, v127
	v_mov_b32_e32 v49, v127
	v_mov_b32_e32 v48, v127
	v_mov_b32_e32 v47, v127
	v_mov_b32_e32 v46, v127
	v_mov_b32_e32 v45, v127
	v_mov_b32_e32 v44, v127
	v_mov_b32_e32 v35, v127
	v_mov_b32_e32 v34, v127
	v_mov_b32_e32 v33, v127
	v_mov_b32_e32 v32, v127
	v_mov_b32_e32 v31, v127
	v_mov_b32_e32 v30, v127
	v_mov_b32_e32 v29, v127
	v_mov_b32_e32 v28, v127
	v_mov_b32_e32 v19, v127
	v_mov_b32_e32 v18, v127
	v_mov_b32_e32 v17, v127
	v_mov_b32_e32 v16, v127
	v_mov_b32_e32 v15, v127
	v_mov_b32_e32 v14, v127
	v_mov_b32_e32 v13, v127
	v_mov_b32_e32 v12, v127
	v_mov_b32_e32 v59, v127
	v_mov_b32_e32 v58, v127
	v_mov_b32_e32 v57, v127
	v_mov_b32_e32 v56, v127
	v_mov_b32_e32 v55, v127
	v_mov_b32_e32 v54, v127
	v_mov_b32_e32 v53, v127
	v_mov_b32_e32 v52, v127
	v_mov_b32_e32 v43, v127
	v_mov_b32_e32 v42, v127
	v_mov_b32_e32 v41, v127
	v_mov_b32_e32 v40, v127
	v_mov_b32_e32 v39, v127
	v_mov_b32_e32 v38, v127
	v_mov_b32_e32 v37, v127
	v_mov_b32_e32 v36, v127
	v_mov_b32_e32 v27, v127
	v_mov_b32_e32 v26, v127
	v_mov_b32_e32 v25, v127
	v_mov_b32_e32 v24, v127
	v_mov_b32_e32 v23, v127
	v_mov_b32_e32 v22, v127
	v_mov_b32_e32 v21, v127
	v_mov_b32_e32 v20, v127
	v_mov_b32_e32 v11, v127
	v_mov_b32_e32 v10, v127
	v_mov_b32_e32 v9, v127
	v_mov_b32_e32 v8, v127
	v_mov_b32_e32 v7, v127
	v_mov_b32_e32 v6, v127
	v_mov_b32_e32 v5, v127
	v_mov_b32_e32 v4, v127
	s_branch .LBB0_372
.Lzs_16:
	v_mov_b32_e32 v4, 0
	v_lshl_add_u64 v[132:133], v[132:133], 0, s[26:27]
	v_lshl_add_u64 v[134:135], v[134:135], 0, s[22:23]
	s_mov_b32 s12, 0
	v_mov_b32_e32 v5, v4
	v_mov_b32_e32 v6, v4
	v_mov_b32_e32 v7, v4
	v_mov_b32_e32 v8, v4
	v_mov_b32_e32 v9, v4
	v_mov_b32_e32 v10, v4
	v_mov_b32_e32 v11, v4
	v_mov_b32_e32 v20, v4
	v_mov_b32_e32 v21, v4
	v_mov_b32_e32 v22, v4
	v_mov_b32_e32 v23, v4
	v_mov_b32_e32 v24, v4
	v_mov_b32_e32 v25, v4
	v_mov_b32_e32 v26, v4
	v_mov_b32_e32 v27, v4
	v_mov_b32_e32 v36, v4
	v_mov_b32_e32 v37, v4
	v_mov_b32_e32 v38, v4
	v_mov_b32_e32 v39, v4
	v_mov_b32_e32 v40, v4
	v_mov_b32_e32 v41, v4
	v_mov_b32_e32 v42, v4
	v_mov_b32_e32 v43, v4
	v_mov_b32_e32 v52, v4
	v_mov_b32_e32 v53, v4
	v_mov_b32_e32 v54, v4
	v_mov_b32_e32 v55, v4
	v_mov_b32_e32 v56, v4
	v_mov_b32_e32 v57, v4
	v_mov_b32_e32 v58, v4
	v_mov_b32_e32 v59, v4
	v_mov_b32_e32 v12, v4
	v_mov_b32_e32 v13, v4
	v_mov_b32_e32 v14, v4
	v_mov_b32_e32 v15, v4
	v_mov_b32_e32 v16, v4
	v_mov_b32_e32 v17, v4
	v_mov_b32_e32 v18, v4
	v_mov_b32_e32 v19, v4
	v_mov_b32_e32 v28, v4
	v_mov_b32_e32 v29, v4
	v_mov_b32_e32 v30, v4
	v_mov_b32_e32 v31, v4
	v_mov_b32_e32 v32, v4
	v_mov_b32_e32 v33, v4
	v_mov_b32_e32 v34, v4
	v_mov_b32_e32 v35, v4
	v_mov_b32_e32 v44, v4
	v_mov_b32_e32 v45, v4
	v_mov_b32_e32 v46, v4
	v_mov_b32_e32 v47, v4
	v_mov_b32_e32 v48, v4
	v_mov_b32_e32 v49, v4
	v_mov_b32_e32 v50, v4
	v_mov_b32_e32 v51, v4
	v_mov_b32_e32 v60, v4
	v_mov_b32_e32 v61, v4
	v_mov_b32_e32 v62, v4
	v_mov_b32_e32 v63, v4
	v_mov_b32_e32 v64, v4
	v_mov_b32_e32 v65, v4
	v_mov_b32_e32 v66, v4
	v_mov_b32_e32 v67, v4
	v_mov_b32_e32 v68, v4
	v_mov_b32_e32 v69, v4
	v_mov_b32_e32 v70, v4
	v_mov_b32_e32 v71, v4
	v_mov_b32_e32 v72, v4
	v_mov_b32_e32 v73, v4
	v_mov_b32_e32 v74, v4
	v_mov_b32_e32 v75, v4
	v_mov_b32_e32 v84, v4
	v_mov_b32_e32 v85, v4
	v_mov_b32_e32 v86, v4
	v_mov_b32_e32 v87, v4
	v_mov_b32_e32 v88, v4
	v_mov_b32_e32 v89, v4
	v_mov_b32_e32 v90, v4
	v_mov_b32_e32 v91, v4
	v_mov_b32_e32 v100, v4
	v_mov_b32_e32 v101, v4
	v_mov_b32_e32 v102, v4
	v_mov_b32_e32 v103, v4
	v_mov_b32_e32 v104, v4
	v_mov_b32_e32 v105, v4
	v_mov_b32_e32 v106, v4
	v_mov_b32_e32 v107, v4
	v_mov_b32_e32 v116, v4
	v_mov_b32_e32 v117, v4
	v_mov_b32_e32 v118, v4
	v_mov_b32_e32 v119, v4
	v_mov_b32_e32 v120, v4
	v_mov_b32_e32 v121, v4
	v_mov_b32_e32 v122, v4
	v_mov_b32_e32 v123, v4
	v_mov_b32_e32 v76, v4
	v_mov_b32_e32 v77, v4
	v_mov_b32_e32 v78, v4
	v_mov_b32_e32 v79, v4
	v_mov_b32_e32 v80, v4
	v_mov_b32_e32 v81, v4
	v_mov_b32_e32 v82, v4
	v_mov_b32_e32 v83, v4
	v_mov_b32_e32 v92, v4
	v_mov_b32_e32 v93, v4
	v_mov_b32_e32 v94, v4
	v_mov_b32_e32 v95, v4
	v_mov_b32_e32 v96, v4
	v_mov_b32_e32 v97, v4
	v_mov_b32_e32 v98, v4
	v_mov_b32_e32 v99, v4
	v_mov_b32_e32 v108, v4
	v_mov_b32_e32 v109, v4
	v_mov_b32_e32 v110, v4
	v_mov_b32_e32 v111, v4
	v_mov_b32_e32 v112, v4
	v_mov_b32_e32 v113, v4
	v_mov_b32_e32 v114, v4
	v_mov_b32_e32 v115, v4
	v_mov_b32_e32 v128, v4
	v_mov_b32_e32 v129, v4
	v_mov_b32_e32 v130, v4
	v_mov_b32_e32 v131, v4
	v_mov_b32_e32 v124, v4
	v_mov_b32_e32 v125, v4
	v_mov_b32_e32 v126, v4
	v_mov_b32_e32 v127, v4
	.p2align	6

; template <class Epi, class Sched, bool ALIGN_EPI = false, bool SP2 = false>
; __device__ __forceinline__ void gemm_phase(PG8_LAS unsigned char* lds, const Gemm g, const Sched& S, const Epi& E) {
;     ...
;         const bool has_next = S.next(ui + 1, nxt);
;         const char* nA = has_next ? (const char*)g.A + (size_t)nxt.pm * tstep : cA; const char* nB = has_next ? (const char*)g.Bt + (size_t)nxt.pn * tstep : cB;
;         for (int t = 0; t < nt; t += 2) {
;             const bool last = (t == nt - 2);
;             const char* a1 = cA + (size_t)(t + 1) * kstep;
;             const char* a2 = last ? nA : cA + (size_t)(t + 2) * kstep; const char* b2 = last ? nB : cB + (size_t)(t + 2) * kstep;
;             const char* a3 = a2 + kstep; const char* b3 = b2 + kstep;
;     ...
; #pragma unroll
;         for (int a = 0; a < 2; ++a)
; #pragma unroll
;             for (int b = 0; b < 2; ++b)
; #pragma unroll
;                 for (int m = 0; m < 4; ++m)
; #pragma unroll
;                     for (int n = 0; n < 2; ++n) acc[a][b][m][n] = (f32x4){0.f, 0.f, 0.f, 0.f};
;         cur = nxt; cA = nA; cB = nB; ++ui;
.LBB0_452:
	s_andn2_b64 vcc, exec, s[26:27]
	s_waitcnt lgkmcnt(0)
	s_cbranch_vccz .Lzs_15
	v_mov_b32_e32 v127, 0
	v_mov_b32_e32 v126, v127
	v_mov_b32_e32 v125, v127
	v_mov_b32_e32 v124, v127
	v_mov_b32_e32 v123, v127
	v_mov_b32_e32 v122, v127
	v_mov_b32_e32 v121, v127
	v_mov_b32_e32 v120, v127
	v_mov_b32_e32 v111, v127
	v_mov_b32_e32 v110, v127
	v_mov_b32_e32 v109, v127
	v_mov_b32_e32 v108, v127
	v_mov_b32_e32 v107, v127
	v_mov_b32_e32 v106, v127
	v_mov_b32_e32 v105, v127
	v_mov_b32_e32 v104, v127
	v_mov_b32_e32 v95, v127
	v_mov_b32_e32 v94, v127
	v_mov_b32_e32 v93, v127
	v_mov_b32_e32 v92, v127
	v_mov_b32_e32 v91, v127
	v_mov_b32_e32 v90, v127
	v_mov_b32_e32 v89, v127
	v_mov_b32_e32 v88, v127
	v_mov_b32_e32 v79, v127
	v_mov_b32_e32 v78, v127
	v_mov_b32_e32 v77, v127
	v_mov_b32_e32 v76, v127
	v_mov_b32_e32 v75, v127
	v_mov_b32_e32 v74, v127
	v_mov_b32_e32 v73, v127
	v_mov_b32_e32 v72, v127
	v_mov_b32_e32 v119, v127
	v_mov_b32_e32 v118, v127
	v_mov_b32_e32 v117, v127
	v_mov_b32_e32 v116, v127
	v_mov_b32_e32 v115, v127
	v_mov_b32_e32 v114, v127
	v_mov_b32_e32 v113, v127
	v_mov_b32_e32 v112, v127
	v_mov_b32_e32 v103, v127
	v_mov_b32_e32 v102, v127
	v_mov_b32_e32 v101, v127
	v_mov_b32_e32 v100, v127
	v_mov_b32_e32 v99, v127
	v_mov_b32_e32 v98, v127
	v_mov_b32_e32 v97, v127
	v_mov_b32_e32 v96, v127
	v_mov_b32_e32 v87, v127
	v_mov_b32_e32 v86, v127
	v_mov_b32_e32 v85, v127
	v_mov_b32_e32 v84, v127
	v_mov_b32_e32 v83, v127
	v_mov_b32_e32 v82, v127
	v_mov_b32_e32 v81, v127
	v_mov_b32_e32 v80, v127
	v_mov_b32_e32 v71, v127
	v_mov_b32_e32 v70, v127
	v_mov_b32_e32 v69, v127
	v_mov_b32_e32 v68, v127
	v_mov_b32_e32 v67, v127
	v_mov_b32_e32 v66, v127
	v_mov_b32_e32 v65, v127
	v_mov_b32_e32 v64, v127
	v_mov_b32_e32 v63, v127
	v_mov_b32_e32 v62, v127
	v_mov_b32_e32 v61, v127
	v_mov_b32_e32 v60, v127
	v_mov_b32_e32 v59, v127
	v_mov_b32_e32 v58, v127
	v_mov_b32_e32 v57, v127
	v_mov_b32_e32 v56, v127
	v_mov_b32_e32 v47, v127
	v_mov_b32_e32 v46, v127
	v_mov_b32_e32 v45, v127
	v_mov_b32_e32 v44, v127
	v_mov_b32_e32 v43, v127
	v_mov_b32_e32 v42, v127
	v_mov_b32_e32 v41, v127
	v_mov_b32_e32 v40, v127
	v_mov_b32_e32 v31, v127
	v_mov_b32_e32 v30, v127
	v_mov_b32_e32 v29, v127
	v_mov_b32_e32 v28, v127
	v_mov_b32_e32 v27, v127
	v_mov_b32_e32 v26, v127
	v_mov_b32_e32 v25, v127
	v_mov_b32_e32 v24, v127
	v_mov_b32_e32 v15, v127
	v_mov_b32_e32 v14, v127
	v_mov_b32_e32 v13, v127
	v_mov_b32_e32 v12, v127
	v_mov_b32_e32 v11, v127
	v_mov_b32_e32 v10, v127
	v_mov_b32_e32 v9, v127
	v_mov_b32_e32 v8, v127
	v_mov_b32_e32 v55, v127
	v_mov_b32_e32 v54, v127
	v_mov_b32_e32 v53, v127
	v_mov_b32_e32 v52, v127
	v_mov_b32_e32 v51, v127
	v_mov_b32_e32 v50, v127
	v_mov_b32_e32 v49, v127
	v_mov_b32_e32 v48, v127
	v_mov_b32_e32 v39, v127
	v_mov_b32_e32 v38, v127
	v_mov_b32_e32 v37, v127
	v_mov_b32_e32 v36, v127
	v_mov_b32_e32 v35, v127
	v_mov_b32_e32 v34, v127
	v_mov_b32_e32 v33, v127
	v_mov_b32_e32 v32, v127
	v_mov_b32_e32 v23, v127
	v_mov_b32_e32 v22, v127
	v_mov_b32_e32 v21, v127
	v_mov_b32_e32 v20, v127
	v_mov_b32_e32 v19, v127
	v_mov_b32_e32 v18, v127
	v_mov_b32_e32 v17, v127
	v_mov_b32_e32 v16, v127
	v_mov_b32_e32 v7, v127
	v_mov_b32_e32 v6, v127
	v_mov_b32_e32 v5, v127
	v_mov_b32_e32 v4, v127
	v_mov_b32_e32 v3, v127
	v_mov_b32_e32 v2, v127
	v_mov_b32_e32 v1, v127
	v_mov_b32_e32 v0, v127
	s_branch .LBB0_455
.Lzs_15:
	v_mov_b32_e32 v0, 0
	v_lshl_add_u64 v[128:129], v[128:129], 0, s[34:35]
	v_lshl_add_u64 v[130:131], v[130:131], 0, s[24:25]
	s_mov_b32 s12, 0
	v_mov_b32_e32 v1, v0
	v_mov_b32_e32 v2, v0
	v_mov_b32_e32 v3, v0
	v_mov_b32_e32 v4, v0
	v_mov_b32_e32 v5, v0
	v_mov_b32_e32 v6, v0
	v_mov_b32_e32 v7, v0
	v_mov_b32_e32 v16, v0
	v_mov_b32_e32 v17, v0
	v_mov_b32_e32 v18, v0
	v_mov_b32_e32 v19, v0
	v_mov_b32_e32 v20, v0
	v_mov_b32_e32 v21, v0
	v_mov_b32_e32 v22, v0
	v_mov_b32_e32 v23, v0
	v_mov_b32_e32 v32, v0
	v_mov_b32_e32 v33, v0
	v_mov_b32_e32 v34, v0
	v_mov_b32_e32 v35, v0
	v_mov_b32_e32 v36, v0
	v_mov_b32_e32 v37, v0
	v_mov_b32_e32 v38, v0
	v_mov_b32_e32 v39, v0
	v_mov_b32_e32 v48, v0
	v_mov_b32_e32 v49, v0
	v_mov_b32_e32 v50, v0
	v_mov_b32_e32 v51, v0
	v_mov_b32_e32 v52, v0
	v_mov_b32_e32 v53, v0
	v_mov_b32_e32 v54, v0
	v_mov_b32_e32 v55, v0
	v_mov_b32_e32 v8, v0
	v_mov_b32_e32 v9, v0
	v_mov_b32_e32 v10, v0
	v_mov_b32_e32 v11, v0
	v_mov_b32_e32 v12, v0
	v_mov_b32_e32 v13, v0
	v_mov_b32_e32 v14, v0
	v_mov_b32_e32 v15, v0
	v_mov_b32_e32 v24, v0
	v_mov_b32_e32 v25, v0
	v_mov_b32_e32 v26, v0
	v_mov_b32_e32 v27, v0
	v_mov_b32_e32 v28, v0
	v_mov_b32_e32 v29, v0
	v_mov_b32_e32 v30, v0
	v_mov_b32_e32 v31, v0
	v_mov_b32_e32 v40, v0
	v_mov_b32_e32 v41, v0
	v_mov_b32_e32 v42, v0
	v_mov_b32_e32 v43, v0
	v_mov_b32_e32 v44, v0
	v_mov_b32_e32 v45, v0
	v_mov_b32_e32 v46, v0
	v_mov_b32_e32 v47, v0
	v_mov_b32_e32 v56, v0
	v_mov_b32_e32 v57, v0
	v_mov_b32_e32 v58, v0
	v_mov_b32_e32 v59, v0
	v_mov_b32_e32 v60, v0
	v_mov_b32_e32 v61, v0
	v_mov_b32_e32 v62, v0
	v_mov_b32_e32 v63, v0
	v_mov_b32_e32 v64, v0
	v_mov_b32_e32 v65, v0
	v_mov_b32_e32 v66, v0
	v_mov_b32_e32 v67, v0
	v_mov_b32_e32 v68, v0
	v_mov_b32_e32 v69, v0
	v_mov_b32_e32 v70, v0
	v_mov_b32_e32 v71, v0
	v_mov_b32_e32 v80, v0
	v_mov_b32_e32 v81, v0
	v_mov_b32_e32 v82, v0
	v_mov_b32_e32 v83, v0
	v_mov_b32_e32 v84, v0
	v_mov_b32_e32 v85, v0
	v_mov_b32_e32 v86, v0
	v_mov_b32_e32 v87, v0
	v_mov_b32_e32 v96, v0
	v_mov_b32_e32 v97, v0
	v_mov_b32_e32 v98, v0
	v_mov_b32_e32 v99, v0
	v_mov_b32_e32 v100, v0
	v_mov_b32_e32 v101, v0
	v_mov_b32_e32 v102, v0
	v_mov_b32_e32 v103, v0
	v_mov_b32_e32 v112, v0
	v_mov_b32_e32 v113, v0
	v_mov_b32_e32 v114, v0
	v_mov_b32_e32 v115, v0
	v_mov_b32_e32 v116, v0
	v_mov_b32_e32 v117, v0
	v_mov_b32_e32 v118, v0
	v_mov_b32_e32 v119, v0
	v_mov_b32_e32 v72, v0
	v_mov_b32_e32 v73, v0
	v_mov_b32_e32 v74, v0
	v_mov_b32_e32 v75, v0
	v_mov_b32_e32 v76, v0
	v_mov_b32_e32 v77, v0
	v_mov_b32_e32 v78, v0
	v_mov_b32_e32 v79, v0
	v_mov_b32_e32 v88, v0
	v_mov_b32_e32 v89, v0
	v_mov_b32_e32 v90, v0
	v_mov_b32_e32 v91, v0
	v_mov_b32_e32 v92, v0
	v_mov_b32_e32 v93, v0
	v_mov_b32_e32 v94, v0
	v_mov_b32_e32 v95, v0
	v_mov_b32_e32 v104, v0
	v_mov_b32_e32 v105, v0
	v_mov_b32_e32 v106, v0
	v_mov_b32_e32 v107, v0
	v_mov_b32_e32 v108, v0
	v_mov_b32_e32 v109, v0
	v_mov_b32_e32 v110, v0
	v_mov_b32_e32 v111, v0
	v_mov_b32_e32 v120, v0
	v_mov_b32_e32 v121, v0
	v_mov_b32_e32 v122, v0
	v_mov_b32_e32 v123, v0
	v_mov_b32_e32 v124, v0
	v_mov_b32_e32 v125, v0
	v_mov_b32_e32 v126, v0
	v_mov_b32_e32 v127, v0
	.p2align	6

; template <class Epi, class Sched, bool ALIGN_EPI = false, bool SP2 = false>
; __device__ __forceinline__ void gemm_phase(PG8_LAS unsigned char* lds, const Gemm g, const Sched& S, const Epi& E) {
;     ...
;         const bool has_next = S.next(ui + 1, nxt);
;         const char* nA = has_next ? (const char*)g.A + (size_t)nxt.pm * tstep : cA; const char* nB = has_next ? (const char*)g.Bt + (size_t)nxt.pn * tstep : cB;
;         for (int t = 0; t < nt; t += 2) {
;             const bool last = (t == nt - 2);
;             const char* a1 = cA + (size_t)(t + 1) * kstep;
;             const char* a2 = last ? nA : cA + (size_t)(t + 2) * kstep; const char* b2 = last ? nB : cB + (size_t)(t + 2) * kstep;
;             const char* a3 = a2 + kstep; const char* b3 = b2 + kstep;
;     ...
; #pragma unroll
;         for (int a = 0; a < 2; ++a)
; #pragma unroll
;             for (int b = 0; b < 2; ++b)
; #pragma unroll
;                 for (int m = 0; m < 4; ++m)
; #pragma unroll
;                     for (int n = 0; n < 2; ++n) acc[a][b][m][n] = (f32x4){0.f, 0.f, 0.f, 0.f};
;         cur = nxt; cA = nA; cB = nB; ++ui;
.LBB0_633:
	s_andn2_b64 vcc, exec, s[26:27]
	s_cbranch_vccz .Lzs_14
	v_mov_b32_e32 v143, 0
	v_mov_b32_e32 v142, v143
	v_mov_b32_e32 v141, v143
	v_mov_b32_e32 v140, v143
	v_mov_b32_e32 v139, v143
	v_mov_b32_e32 v138, v143
	v_mov_b32_e32 v137, v143
	v_mov_b32_e32 v136, v143
	v_mov_b32_e32 v119, v143
	v_mov_b32_e32 v118, v143
	v_mov_b32_e32 v117, v143
	v_mov_b32_e32 v116, v143
	v_mov_b32_e32 v115, v143
	v_mov_b32_e32 v114, v143
	v_mov_b32_e32 v113, v143
	v_mov_b32_e32 v112, v143
	v_mov_b32_e32 v103, v143
	v_mov_b32_e32 v102, v143
	v_mov_b32_e32 v101, v143
	v_mov_b32_e32 v100, v143
	v_mov_b32_e32 v99, v143
	v_mov_b32_e32 v98, v143
	v_mov_b32_e32 v97, v143
	v_mov_b32_e32 v96, v143
	v_mov_b32_e32 v79, v143
	v_mov_b32_e32 v78, v143
	v_mov_b32_e32 v77, v143
	v_mov_b32_e32 v76, v143
	v_mov_b32_e32 v75, v143
	v_mov_b32_e32 v74, v143
	v_mov_b32_e32 v73, v143
	v_mov_b32_e32 v72, v143
	v_mov_b32_e32 v127, v143
	v_mov_b32_e32 v126, v143
	v_mov_b32_e32 v125, v143
	v_mov_b32_e32 v124, v143
	v_mov_b32_e32 v123, v143
	v_mov_b32_e32 v122, v143
	v_mov_b32_e32 v121, v143
	v_mov_b32_e32 v120, v143
	v_mov_b32_e32 v111, v143
	v_mov_b32_e32 v110, v143
	v_mov_b32_e32 v109, v143
	v_mov_b32_e32 v108, v143
	v_mov_b32_e32 v107, v143
	v_mov_b32_e32 v106, v143
	v_mov_b32_e32 v105, v143
	v_mov_b32_e32 v104, v143
	v_mov_b32_e32 v87, v143
	v_mov_b32_e32 v86, v143
	v_mov_b32_e32 v85, v143
	v_mov_b32_e32 v84, v143
	v_mov_b32_e32 v83, v143
	v_mov_b32_e32 v82, v143
	v_mov_b32_e32 v81, v143
	v_mov_b32_e32 v80, v143
	v_mov_b32_e32 v71, v143
	v_mov_b32_e32 v70, v143
	v_mov_b32_e32 v69, v143
	v_mov_b32_e32 v68, v143
	v_mov_b32_e32 v67, v143
	v_mov_b32_e32 v66, v143
	v_mov_b32_e32 v65, v143
	v_mov_b32_e32 v64, v143
	v_mov_b32_e32 v63, v143
	v_mov_b32_e32 v62, v143
	v_mov_b32_e32 v61, v143
	v_mov_b32_e32 v60, v143
	v_mov_b32_e32 v59, v143
	v_mov_b32_e32 v58, v143
	v_mov_b32_e32 v57, v143
	v_mov_b32_e32 v56, v143
	v_mov_b32_e32 v47, v143
	v_mov_b32_e32 v46, v143
	v_mov_b32_e32 v45, v143
	v_mov_b32_e32 v44, v143
	v_mov_b32_e32 v43, v143
	v_mov_b32_e32 v42, v143
	v_mov_b32_e32 v41, v143
	v_mov_b32_e32 v40, v143
	v_mov_b32_e32 v31, v143
	v_mov_b32_e32 v30, v143
	v_mov_b32_e32 v29, v143
	v_mov_b32_e32 v28, v143
	v_mov_b32_e32 v27, v143
	v_mov_b32_e32 v26, v143
	v_mov_b32_e32 v25, v143
	v_mov_b32_e32 v24, v143
	v_mov_b32_e32 v15, v143
	v_mov_b32_e32 v14, v143
	v_mov_b32_e32 v13, v143
	v_mov_b32_e32 v12, v143
	v_mov_b32_e32 v11, v143
	v_mov_b32_e32 v10, v143
	v_mov_b32_e32 v9, v143
	v_mov_b32_e32 v8, v143
	v_mov_b32_e32 v55, v143
	v_mov_b32_e32 v54, v143
	v_mov_b32_e32 v53, v143
	v_mov_b32_e32 v52, v143
	v_mov_b32_e32 v51, v143
	v_mov_b32_e32 v50, v143
	v_mov_b32_e32 v49, v143
	v_mov_b32_e32 v48, v143
	v_mov_b32_e32 v39, v143
	v_mov_b32_e32 v38, v143
	v_mov_b32_e32 v37, v143
	v_mov_b32_e32 v36, v143
	v_mov_b32_e32 v35, v143
	v_mov_b32_e32 v34, v143
	v_mov_b32_e32 v33, v143
	v_mov_b32_e32 v32, v143
	v_mov_b32_e32 v23, v143
	v_mov_b32_e32 v22, v143
	v_mov_b32_e32 v21, v143
	v_mov_b32_e32 v20, v143
	v_mov_b32_e32 v19, v143
	v_mov_b32_e32 v18, v143
	v_mov_b32_e32 v17, v143
	v_mov_b32_e32 v16, v143
	v_mov_b32_e32 v7, v143
	v_mov_b32_e32 v6, v143
	v_mov_b32_e32 v5, v143
	v_mov_b32_e32 v4, v143
	v_mov_b32_e32 v3, v143
	v_mov_b32_e32 v2, v143
	v_mov_b32_e32 v1, v143
	v_mov_b32_e32 v0, v143
	s_branch .LBB0_636
.Lzs_14:
	v_mov_b32_e32 v0, 0
	v_lshl_add_u64 v[88:89], v[88:89], 0, s[30:31]
	v_lshl_add_u64 v[90:91], v[90:91], 0, s[24:25]
	s_mov_b32 s10, 0
	v_mov_b32_e32 v1, v0
	v_mov_b32_e32 v2, v0
	v_mov_b32_e32 v3, v0
	v_mov_b32_e32 v4, v0
	v_mov_b32_e32 v5, v0
	v_mov_b32_e32 v6, v0
	v_mov_b32_e32 v7, v0
	v_mov_b32_e32 v16, v0
	v_mov_b32_e32 v17, v0
	v_mov_b32_e32 v18, v0
	v_mov_b32_e32 v19, v0
	v_mov_b32_e32 v20, v0
	v_mov_b32_e32 v21, v0
	v_mov_b32_e32 v22, v0
	v_mov_b32_e32 v23, v0
	v_mov_b32_e32 v32, v0
	v_mov_b32_e32 v33, v0
	v_mov_b32_e32 v34, v0
	v_mov_b32_e32 v35, v0
	v_mov_b32_e32 v36, v0
	v_mov_b32_e32 v37, v0
	v_mov_b32_e32 v38, v0
	v_mov_b32_e32 v39, v0
	v_mov_b32_e32 v48, v0
	v_mov_b32_e32 v49, v0
	v_mov_b32_e32 v50, v0
	v_mov_b32_e32 v51, v0
	v_mov_b32_e32 v52, v0
	v_mov_b32_e32 v53, v0
	v_mov_b32_e32 v54, v0
	v_mov_b32_e32 v55, v0
	v_mov_b32_e32 v8, v0
	v_mov_b32_e32 v9, v0
	v_mov_b32_e32 v10, v0
	v_mov_b32_e32 v11, v0
	v_mov_b32_e32 v12, v0
	v_mov_b32_e32 v13, v0
	v_mov_b32_e32 v14, v0
	v_mov_b32_e32 v15, v0
	v_mov_b32_e32 v24, v0
	v_mov_b32_e32 v25, v0
	v_mov_b32_e32 v26, v0
	v_mov_b32_e32 v27, v0
	v_mov_b32_e32 v28, v0
	v_mov_b32_e32 v29, v0
	v_mov_b32_e32 v30, v0
	v_mov_b32_e32 v31, v0
	v_mov_b32_e32 v40, v0
	v_mov_b32_e32 v41, v0
	v_mov_b32_e32 v42, v0
	v_mov_b32_e32 v43, v0
	v_mov_b32_e32 v44, v0
	v_mov_b32_e32 v45, v0
	v_mov_b32_e32 v46, v0
	v_mov_b32_e32 v47, v0
	v_mov_b32_e32 v56, v0
	v_mov_b32_e32 v57, v0
	v_mov_b32_e32 v58, v0
	v_mov_b32_e32 v59, v0
	v_mov_b32_e32 v60, v0
	v_mov_b32_e32 v61, v0
	v_mov_b32_e32 v62, v0
	v_mov_b32_e32 v63, v0
	v_mov_b32_e32 v64, v0
	v_mov_b32_e32 v65, v0
	v_mov_b32_e32 v66, v0
	v_mov_b32_e32 v67, v0
	v_mov_b32_e32 v68, v0
	v_mov_b32_e32 v69, v0
	v_mov_b32_e32 v70, v0
	v_mov_b32_e32 v71, v0
	v_mov_b32_e32 v80, v0
	v_mov_b32_e32 v81, v0
	v_mov_b32_e32 v82, v0
	v_mov_b32_e32 v83, v0
	v_mov_b32_e32 v84, v0
	v_mov_b32_e32 v85, v0
	v_mov_b32_e32 v86, v0
	v_mov_b32_e32 v87, v0
	v_mov_b32_e32 v104, v0
	v_mov_b32_e32 v105, v0
	v_mov_b32_e32 v106, v0
	v_mov_b32_e32 v107, v0
	v_mov_b32_e32 v108, v0
	v_mov_b32_e32 v109, v0
	v_mov_b32_e32 v110, v0
	v_mov_b32_e32 v111, v0
	v_mov_b32_e32 v120, v0
	v_mov_b32_e32 v121, v0
	v_mov_b32_e32 v122, v0
	v_mov_b32_e32 v123, v0
	v_mov_b32_e32 v124, v0
	v_mov_b32_e32 v125, v0
	v_mov_b32_e32 v126, v0
	v_mov_b32_e32 v127, v0
	v_mov_b32_e32 v72, v0
	v_mov_b32_e32 v73, v0
	v_mov_b32_e32 v74, v0
	v_mov_b32_e32 v75, v0
	v_mov_b32_e32 v76, v0
	v_mov_b32_e32 v77, v0
	v_mov_b32_e32 v78, v0
	v_mov_b32_e32 v79, v0
	v_mov_b32_e32 v96, v0
	v_mov_b32_e32 v97, v0
	v_mov_b32_e32 v98, v0
	v_mov_b32_e32 v99, v0
	v_mov_b32_e32 v100, v0
	v_mov_b32_e32 v101, v0
	v_mov_b32_e32 v102, v0
	v_mov_b32_e32 v103, v0
	v_mov_b32_e32 v112, v0
	v_mov_b32_e32 v113, v0
	v_mov_b32_e32 v114, v0
	v_mov_b32_e32 v115, v0
	v_mov_b32_e32 v116, v0
	v_mov_b32_e32 v117, v0
	v_mov_b32_e32 v118, v0
	v_mov_b32_e32 v119, v0
	v_mov_b32_e32 v136, v0
	v_mov_b32_e32 v137, v0
	v_mov_b32_e32 v138, v0
	v_mov_b32_e32 v139, v0
	v_mov_b32_e32 v140, v0
	v_mov_b32_e32 v141, v0
	v_mov_b32_e32 v142, v0
	v_mov_b32_e32 v143, v0
	.p2align	6

; template <class Epi, class Sched, bool ALIGN_EPI = false, bool SP2 = false>
; __device__ __forceinline__ void gemm_phase(PG8_LAS unsigned char* lds, const Gemm g, const Sched& S, const Epi& E) {
;     ...
;         const bool has_next = S.next(ui + 1, nxt);
;         const char* nA = has_next ? (const char*)g.A + (size_t)nxt.pm * tstep : cA; const char* nB = has_next ? (const char*)g.Bt + (size_t)nxt.pn * tstep : cB;
;         for (int t = 0; t < nt; t += 2) {
;             const bool last = (t == nt - 2);
;             const char* a1 = cA + (size_t)(t + 1) * kstep;
;             const char* a2 = last ? nA : cA + (size_t)(t + 2) * kstep; const char* b2 = last ? nB : cB + (size_t)(t + 2) * kstep;
;             const char* a3 = a2 + kstep; const char* b3 = b2 + kstep;
;     ...
; #pragma unroll
;         for (int a = 0; a < 2; ++a)
; #pragma unroll
;             for (int b = 0; b < 2; ++b)
; #pragma unroll
;                 for (int m = 0; m < 4; ++m)
; #pragma unroll
;                     for (int n = 0; n < 2; ++n) acc[a][b][m][n] = (f32x4){0.f, 0.f, 0.f, 0.f};
;         cur = nxt; cA = nA; cB = nB; ++ui;
.LBB0_720:
	s_andn2_b64 vcc, exec, s[20:21]
	s_cbranch_vccz .Lzs_13
	v_mov_b32_e32 v135, 0
	v_mov_b32_e32 v134, v135
	v_mov_b32_e32 v133, v135
	v_mov_b32_e32 v132, v135
	v_mov_b32_e32 v131, v135
	v_mov_b32_e32 v130, v135
	v_mov_b32_e32 v129, v135
	v_mov_b32_e32 v128, v135
	v_mov_b32_e32 v111, v135
	v_mov_b32_e32 v110, v135
	v_mov_b32_e32 v109, v135
	v_mov_b32_e32 v108, v135
	v_mov_b32_e32 v107, v135
	v_mov_b32_e32 v106, v135
	v_mov_b32_e32 v105, v135
	v_mov_b32_e32 v104, v135
	v_mov_b32_e32 v95, v135
	v_mov_b32_e32 v94, v135
	v_mov_b32_e32 v93, v135
	v_mov_b32_e32 v92, v135
	v_mov_b32_e32 v91, v135
	v_mov_b32_e32 v90, v135
	v_mov_b32_e32 v89, v135
	v_mov_b32_e32 v88, v135
	v_mov_b32_e32 v79, v135
	v_mov_b32_e32 v78, v135
	v_mov_b32_e32 v77, v135
	v_mov_b32_e32 v76, v135
	v_mov_b32_e32 v75, v135
	v_mov_b32_e32 v74, v135
	v_mov_b32_e32 v73, v135
	v_mov_b32_e32 v72, v135
	v_mov_b32_e32 v127, v135
	v_mov_b32_e32 v126, v135
	v_mov_b32_e32 v125, v135
	v_mov_b32_e32 v124, v135
	v_mov_b32_e32 v123, v135
	v_mov_b32_e32 v122, v135
	v_mov_b32_e32 v121, v135
	v_mov_b32_e32 v120, v135
	v_mov_b32_e32 v103, v135
	v_mov_b32_e32 v102, v135
	v_mov_b32_e32 v101, v135
	v_mov_b32_e32 v100, v135
	v_mov_b32_e32 v99, v135
	v_mov_b32_e32 v98, v135
	v_mov_b32_e32 v97, v135
	v_mov_b32_e32 v96, v135
	v_mov_b32_e32 v87, v135
	v_mov_b32_e32 v86, v135
	v_mov_b32_e32 v85, v135
	v_mov_b32_e32 v84, v135
	v_mov_b32_e32 v83, v135
	v_mov_b32_e32 v82, v135
	v_mov_b32_e32 v81, v135
	v_mov_b32_e32 v80, v135
	v_mov_b32_e32 v71, v135
	v_mov_b32_e32 v70, v135
	v_mov_b32_e32 v69, v135
	v_mov_b32_e32 v68, v135
	v_mov_b32_e32 v67, v135
	v_mov_b32_e32 v66, v135
	v_mov_b32_e32 v65, v135
	v_mov_b32_e32 v64, v135
	v_mov_b32_e32 v63, v135
	v_mov_b32_e32 v62, v135
	v_mov_b32_e32 v61, v135
	v_mov_b32_e32 v60, v135
	v_mov_b32_e32 v59, v135
	v_mov_b32_e32 v58, v135
	v_mov_b32_e32 v57, v135
	v_mov_b32_e32 v56, v135
	v_mov_b32_e32 v47, v135
	v_mov_b32_e32 v46, v135
	v_mov_b32_e32 v45, v135
	v_mov_b32_e32 v44, v135
	v_mov_b32_e32 v43, v135
	v_mov_b32_e32 v42, v135
	v_mov_b32_e32 v41, v135
	v_mov_b32_e32 v40, v135
	v_mov_b32_e32 v31, v135
	v_mov_b32_e32 v30, v135
	v_mov_b32_e32 v29, v135
	v_mov_b32_e32 v28, v135
	v_mov_b32_e32 v27, v135
	v_mov_b32_e32 v26, v135
	v_mov_b32_e32 v25, v135
	v_mov_b32_e32 v24, v135
	v_mov_b32_e32 v15, v135
	v_mov_b32_e32 v14, v135
	v_mov_b32_e32 v13, v135
	v_mov_b32_e32 v12, v135
	v_mov_b32_e32 v11, v135
	v_mov_b32_e32 v10, v135
	v_mov_b32_e32 v9, v135
	v_mov_b32_e32 v8, v135
	v_mov_b32_e32 v55, v135
	v_mov_b32_e32 v54, v135
	v_mov_b32_e32 v53, v135
	v_mov_b32_e32 v52, v135
	v_mov_b32_e32 v51, v135
	v_mov_b32_e32 v50, v135
	v_mov_b32_e32 v49, v135
	v_mov_b32_e32 v48, v135
	v_mov_b32_e32 v39, v135
	v_mov_b32_e32 v38, v135
	v_mov_b32_e32 v37, v135
	v_mov_b32_e32 v36, v135
	v_mov_b32_e32 v35, v135
	v_mov_b32_e32 v34, v135
	v_mov_b32_e32 v33, v135
	v_mov_b32_e32 v32, v135
	v_mov_b32_e32 v23, v135
	v_mov_b32_e32 v22, v135
	v_mov_b32_e32 v21, v135
	v_mov_b32_e32 v20, v135
	v_mov_b32_e32 v19, v135
	v_mov_b32_e32 v18, v135
	v_mov_b32_e32 v17, v135
	v_mov_b32_e32 v16, v135
	v_mov_b32_e32 v7, v135
	v_mov_b32_e32 v6, v135
	v_mov_b32_e32 v5, v135
	v_mov_b32_e32 v4, v135
	v_mov_b32_e32 v3, v135
	v_mov_b32_e32 v2, v135
	v_mov_b32_e32 v1, v135
	v_mov_b32_e32 v0, v135
	s_branch .LBB0_723
.Lzs_13:
	v_mov_b32_e32 v0, 0
	v_lshl_add_u64 v[112:113], v[112:113], 0, s[26:27]
	v_lshl_add_u64 v[114:115], v[114:115], 0, s[18:19]
	s_mov_b32 s8, 0
	v_mov_b32_e32 v1, v0
	v_mov_b32_e32 v2, v0
	v_mov_b32_e32 v3, v0
	v_mov_b32_e32 v4, v0
	v_mov_b32_e32 v5, v0
	v_mov_b32_e32 v6, v0
	v_mov_b32_e32 v7, v0
	v_mov_b32_e32 v16, v0
	v_mov_b32_e32 v17, v0
	v_mov_b32_e32 v18, v0
	v_mov_b32_e32 v19, v0
	v_mov_b32_e32 v20, v0
	v_mov_b32_e32 v21, v0
	v_mov_b32_e32 v22, v0
	v_mov_b32_e32 v23, v0
	v_mov_b32_e32 v32, v0
	v_mov_b32_e32 v33, v0
	v_mov_b32_e32 v34, v0
	v_mov_b32_e32 v35, v0
	v_mov_b32_e32 v36, v0
	v_mov_b32_e32 v37, v0
	v_mov_b32_e32 v38, v0
	v_mov_b32_e32 v39, v0
	v_mov_b32_e32 v48, v0
	v_mov_b32_e32 v49, v0
	v_mov_b32_e32 v50, v0
	v_mov_b32_e32 v51, v0
	v_mov_b32_e32 v52, v0
	v_mov_b32_e32 v53, v0
	v_mov_b32_e32 v54, v0
	v_mov_b32_e32 v55, v0
	v_mov_b32_e32 v8, v0
	v_mov_b32_e32 v9, v0
	v_mov_b32_e32 v10, v0
	v_mov_b32_e32 v11, v0
	v_mov_b32_e32 v12, v0
	v_mov_b32_e32 v13, v0
	v_mov_b32_e32 v14, v0
	v_mov_b32_e32 v15, v0
	v_mov_b32_e32 v24, v0
	v_mov_b32_e32 v25, v0
	v_mov_b32_e32 v26, v0
	v_mov_b32_e32 v27, v0
	v_mov_b32_e32 v28, v0
	v_mov_b32_e32 v29, v0
	v_mov_b32_e32 v30, v0
	v_mov_b32_e32 v31, v0
	v_mov_b32_e32 v40, v0
	v_mov_b32_e32 v41, v0
	v_mov_b32_e32 v42, v0
	v_mov_b32_e32 v43, v0
	v_mov_b32_e32 v44, v0
	v_mov_b32_e32 v45, v0
	v_mov_b32_e32 v46, v0
	v_mov_b32_e32 v47, v0
	v_mov_b32_e32 v56, v0
	v_mov_b32_e32 v57, v0
	v_mov_b32_e32 v58, v0
	v_mov_b32_e32 v59, v0
	v_mov_b32_e32 v60, v0
	v_mov_b32_e32 v61, v0
	v_mov_b32_e32 v62, v0
	v_mov_b32_e32 v63, v0
	v_mov_b32_e32 v64, v0
	v_mov_b32_e32 v65, v0
	v_mov_b32_e32 v66, v0
	v_mov_b32_e32 v67, v0
	v_mov_b32_e32 v68, v0
	v_mov_b32_e32 v69, v0
	v_mov_b32_e32 v70, v0
	v_mov_b32_e32 v71, v0
	v_mov_b32_e32 v80, v0
	v_mov_b32_e32 v81, v0
	v_mov_b32_e32 v82, v0
	v_mov_b32_e32 v83, v0
	v_mov_b32_e32 v84, v0
	v_mov_b32_e32 v85, v0
	v_mov_b32_e32 v86, v0
	v_mov_b32_e32 v87, v0
	v_mov_b32_e32 v96, v0
	v_mov_b32_e32 v97, v0
	v_mov_b32_e32 v98, v0
	v_mov_b32_e32 v99, v0
	v_mov_b32_e32 v100, v0
	v_mov_b32_e32 v101, v0
	v_mov_b32_e32 v102, v0
	v_mov_b32_e32 v103, v0
	v_mov_b32_e32 v120, v0
	v_mov_b32_e32 v121, v0
	v_mov_b32_e32 v122, v0
	v_mov_b32_e32 v123, v0
	v_mov_b32_e32 v124, v0
	v_mov_b32_e32 v125, v0
	v_mov_b32_e32 v126, v0
	v_mov_b32_e32 v127, v0
	v_mov_b32_e32 v72, v0
	v_mov_b32_e32 v73, v0
	v_mov_b32_e32 v74, v0
	v_mov_b32_e32 v75, v0
	v_mov_b32_e32 v76, v0
	v_mov_b32_e32 v77, v0
	v_mov_b32_e32 v78, v0
	v_mov_b32_e32 v79, v0
	v_mov_b32_e32 v88, v0
	v_mov_b32_e32 v89, v0
	v_mov_b32_e32 v90, v0
	v_mov_b32_e32 v91, v0
	v_mov_b32_e32 v92, v0
	v_mov_b32_e32 v93, v0
	v_mov_b32_e32 v94, v0
	v_mov_b32_e32 v95, v0
	v_mov_b32_e32 v104, v0
	v_mov_b32_e32 v105, v0
	v_mov_b32_e32 v106, v0
	v_mov_b32_e32 v107, v0
	v_mov_b32_e32 v108, v0
	v_mov_b32_e32 v109, v0
	v_mov_b32_e32 v110, v0
	v_mov_b32_e32 v111, v0
	v_mov_b32_e32 v128, v0
	v_mov_b32_e32 v129, v0
	v_mov_b32_e32 v130, v0
	v_mov_b32_e32 v131, v0
	v_mov_b32_e32 v132, v0
	v_mov_b32_e32 v133, v0
	v_mov_b32_e32 v134, v0
	v_mov_b32_e32 v135, v0
	.p2align	6

; template <class Epi, class Sched, bool ALIGN_EPI = false, bool SP2 = false>
; __device__ __forceinline__ void gemm_phase(PG8_LAS unsigned char* lds, const Gemm g, const Sched& S, const Epi& E) {
;     ...
;         const bool has_next = S.next(ui + 1, nxt);
;         const char* nA = has_next ? (const char*)g.A + (size_t)nxt.pm * tstep : cA; const char* nB = has_next ? (const char*)g.Bt + (size_t)nxt.pn * tstep : cB;
;         for (int t = 0; t < nt; t += 2) {
;             const bool last = (t == nt - 2);
;             const char* a1 = cA + (size_t)(t + 1) * kstep;
;             const char* a2 = last ? nA : cA + (size_t)(t + 2) * kstep; const char* b2 = last ? nB : cB + (size_t)(t + 2) * kstep;
;             const char* a3 = a2 + kstep; const char* b3 = b2 + kstep;
;     ...
; #pragma unroll
;         for (int a = 0; a < 2; ++a)
; #pragma unroll
;             for (int b = 0; b < 2; ++b)
; #pragma unroll
;                 for (int m = 0; m < 4; ++m)
; #pragma unroll
;                     for (int n = 0; n < 2; ++n) acc[a][b][m][n] = (f32x4){0.f, 0.f, 0.f, 0.f};
;         cur = nxt; cA = nA; cB = nB; ++ui;
.LBB0_938:
	s_and_b64 vcc, exec, s[8:9]
	s_waitcnt lgkmcnt(0)
	s_cbranch_vccz .Lzs_12
	v_mov_b32_e32 v123, 0
	v_mov_b32_e32 v122, v123
	v_mov_b32_e32 v121, v123
	v_mov_b32_e32 v120, v123
	v_mov_b32_e32 v127, v123
	v_mov_b32_e32 v126, v123
	v_mov_b32_e32 v125, v123
	v_mov_b32_e32 v124, v123
	v_mov_b32_e32 v111, v123
	v_mov_b32_e32 v110, v123
	v_mov_b32_e32 v109, v123
	v_mov_b32_e32 v108, v123
	v_mov_b32_e32 v107, v123
	v_mov_b32_e32 v106, v123
	v_mov_b32_e32 v105, v123
	v_mov_b32_e32 v104, v123
	v_mov_b32_e32 v95, v123
	v_mov_b32_e32 v94, v123
	v_mov_b32_e32 v93, v123
	v_mov_b32_e32 v92, v123
	v_mov_b32_e32 v91, v123
	v_mov_b32_e32 v90, v123
	v_mov_b32_e32 v89, v123
	v_mov_b32_e32 v88, v123
	v_mov_b32_e32 v79, v123
	v_mov_b32_e32 v78, v123
	v_mov_b32_e32 v77, v123
	v_mov_b32_e32 v76, v123
	v_mov_b32_e32 v75, v123
	v_mov_b32_e32 v74, v123
	v_mov_b32_e32 v73, v123
	v_mov_b32_e32 v72, v123
	v_mov_b32_e32 v119, v123
	v_mov_b32_e32 v118, v123
	v_mov_b32_e32 v117, v123
	v_mov_b32_e32 v116, v123
	v_mov_b32_e32 v115, v123
	v_mov_b32_e32 v114, v123
	v_mov_b32_e32 v113, v123
	v_mov_b32_e32 v112, v123
	v_mov_b32_e32 v103, v123
	v_mov_b32_e32 v102, v123
	v_mov_b32_e32 v101, v123
	v_mov_b32_e32 v100, v123
	v_mov_b32_e32 v99, v123
	v_mov_b32_e32 v98, v123
	v_mov_b32_e32 v97, v123
	v_mov_b32_e32 v96, v123
	v_mov_b32_e32 v87, v123
	v_mov_b32_e32 v86, v123
	v_mov_b32_e32 v85, v123
	v_mov_b32_e32 v84, v123
	v_mov_b32_e32 v83, v123
	v_mov_b32_e32 v82, v123
	v_mov_b32_e32 v81, v123
	v_mov_b32_e32 v80, v123
	v_mov_b32_e32 v71, v123
	v_mov_b32_e32 v70, v123
	v_mov_b32_e32 v69, v123
	v_mov_b32_e32 v68, v123
	v_mov_b32_e32 v67, v123
	v_mov_b32_e32 v66, v123
	v_mov_b32_e32 v65, v123
	v_mov_b32_e32 v64, v123
	v_mov_b32_e32 v63, v123
	v_mov_b32_e32 v62, v123
	v_mov_b32_e32 v61, v123
	v_mov_b32_e32 v60, v123
	v_mov_b32_e32 v59, v123
	v_mov_b32_e32 v58, v123
	v_mov_b32_e32 v57, v123
	v_mov_b32_e32 v56, v123
	v_mov_b32_e32 v47, v123
	v_mov_b32_e32 v46, v123
	v_mov_b32_e32 v45, v123
	v_mov_b32_e32 v44, v123
	v_mov_b32_e32 v43, v123
	v_mov_b32_e32 v42, v123
	v_mov_b32_e32 v41, v123
	v_mov_b32_e32 v40, v123
	v_mov_b32_e32 v31, v123
	v_mov_b32_e32 v30, v123
	v_mov_b32_e32 v29, v123
	v_mov_b32_e32 v28, v123
	v_mov_b32_e32 v27, v123
	v_mov_b32_e32 v26, v123
	v_mov_b32_e32 v25, v123
	v_mov_b32_e32 v24, v123
	v_mov_b32_e32 v15, v123
	v_mov_b32_e32 v14, v123
	v_mov_b32_e32 v13, v123
	v_mov_b32_e32 v12, v123
	v_mov_b32_e32 v11, v123
	v_mov_b32_e32 v10, v123
	v_mov_b32_e32 v9, v123
	v_mov_b32_e32 v8, v123
	v_mov_b32_e32 v55, v123
	v_mov_b32_e32 v54, v123
	v_mov_b32_e32 v53, v123
	v_mov_b32_e32 v52, v123
	v_mov_b32_e32 v51, v123
	v_mov_b32_e32 v50, v123
	v_mov_b32_e32 v49, v123
	v_mov_b32_e32 v48, v123
	v_mov_b32_e32 v39, v123
	v_mov_b32_e32 v38, v123
	v_mov_b32_e32 v37, v123
	v_mov_b32_e32 v36, v123
	v_mov_b32_e32 v35, v123
	v_mov_b32_e32 v34, v123
	v_mov_b32_e32 v33, v123
	v_mov_b32_e32 v32, v123
	v_mov_b32_e32 v23, v123
	v_mov_b32_e32 v22, v123
	v_mov_b32_e32 v21, v123
	v_mov_b32_e32 v20, v123
	v_mov_b32_e32 v19, v123
	v_mov_b32_e32 v18, v123
	v_mov_b32_e32 v17, v123
	v_mov_b32_e32 v16, v123
	v_mov_b32_e32 v7, v123
	v_mov_b32_e32 v6, v123
	v_mov_b32_e32 v5, v123
	v_mov_b32_e32 v4, v123
	v_mov_b32_e32 v3, v123
	v_mov_b32_e32 v2, v123
	v_mov_b32_e32 v1, v123
	v_mov_b32_e32 v0, v123
	s_branch .LBB0_941
.Lzs_12:
	v_mov_b32_e32 v0, 0
	v_lshl_add_u64 v[128:129], v[128:129], 0, s[26:27]
	v_lshl_add_u64 v[130:131], v[130:131], 0, s[22:23]
	s_mov_b32 s12, 0
	v_mov_b32_e32 v1, v0
	v_mov_b32_e32 v2, v0
	v_mov_b32_e32 v3, v0
	v_mov_b32_e32 v4, v0
	v_mov_b32_e32 v5, v0
	v_mov_b32_e32 v6, v0
	v_mov_b32_e32 v7, v0
	v_mov_b32_e32 v16, v0
	v_mov_b32_e32 v17, v0
	v_mov_b32_e32 v18, v0
	v_mov_b32_e32 v19, v0
	v_mov_b32_e32 v20, v0
	v_mov_b32_e32 v21, v0
	v_mov_b32_e32 v22, v0
	v_mov_b32_e32 v23, v0
	v_mov_b32_e32 v32, v0
	v_mov_b32_e32 v33, v0
	v_mov_b32_e32 v34, v0
	v_mov_b32_e32 v35, v0
	v_mov_b32_e32 v36, v0
	v_mov_b32_e32 v37, v0
	v_mov_b32_e32 v38, v0
	v_mov_b32_e32 v39, v0
	v_mov_b32_e32 v48, v0
	v_mov_b32_e32 v49, v0
	v_mov_b32_e32 v50, v0
	v_mov_b32_e32 v51, v0
	v_mov_b32_e32 v52, v0
	v_mov_b32_e32 v53, v0
	v_mov_b32_e32 v54, v0
	v_mov_b32_e32 v55, v0
	v_mov_b32_e32 v8, v0
	v_mov_b32_e32 v9, v0
	v_mov_b32_e32 v10, v0
	v_mov_b32_e32 v11, v0
	v_mov_b32_e32 v12, v0
	v_mov_b32_e32 v13, v0
	v_mov_b32_e32 v14, v0
	v_mov_b32_e32 v15, v0
	v_mov_b32_e32 v24, v0
	v_mov_b32_e32 v25, v0
	v_mov_b32_e32 v26, v0
	v_mov_b32_e32 v27, v0
	v_mov_b32_e32 v28, v0
	v_mov_b32_e32 v29, v0
	v_mov_b32_e32 v30, v0
	v_mov_b32_e32 v31, v0
	v_mov_b32_e32 v40, v0
	v_mov_b32_e32 v41, v0
	v_mov_b32_e32 v42, v0
	v_mov_b32_e32 v43, v0
	v_mov_b32_e32 v44, v0
	v_mov_b32_e32 v45, v0
	v_mov_b32_e32 v46, v0
	v_mov_b32_e32 v47, v0
	v_mov_b32_e32 v56, v0
	v_mov_b32_e32 v57, v0
	v_mov_b32_e32 v58, v0
	v_mov_b32_e32 v59, v0
	v_mov_b32_e32 v60, v0
	v_mov_b32_e32 v61, v0
	v_mov_b32_e32 v62, v0
	v_mov_b32_e32 v63, v0
	v_mov_b32_e32 v64, v0
	v_mov_b32_e32 v65, v0
	v_mov_b32_e32 v66, v0
	v_mov_b32_e32 v67, v0
	v_mov_b32_e32 v68, v0
	v_mov_b32_e32 v69, v0
	v_mov_b32_e32 v70, v0
	v_mov_b32_e32 v71, v0
	v_mov_b32_e32 v80, v0
	v_mov_b32_e32 v81, v0
	v_mov_b32_e32 v82, v0
	v_mov_b32_e32 v83, v0
	v_mov_b32_e32 v84, v0
	v_mov_b32_e32 v85, v0
	v_mov_b32_e32 v86, v0
	v_mov_b32_e32 v87, v0
	v_mov_b32_e32 v96, v0
	v_mov_b32_e32 v97, v0
	v_mov_b32_e32 v98, v0
	v_mov_b32_e32 v99, v0
	v_mov_b32_e32 v100, v0
	v_mov_b32_e32 v101, v0
	v_mov_b32_e32 v102, v0
	v_mov_b32_e32 v103, v0
	v_mov_b32_e32 v112, v0
	v_mov_b32_e32 v113, v0
	v_mov_b32_e32 v114, v0
	v_mov_b32_e32 v115, v0
	v_mov_b32_e32 v116, v0
	v_mov_b32_e32 v117, v0
	v_mov_b32_e32 v118, v0
	v_mov_b32_e32 v119, v0
	v_mov_b32_e32 v72, v0
	v_mov_b32_e32 v73, v0
	v_mov_b32_e32 v74, v0
	v_mov_b32_e32 v75, v0
	v_mov_b32_e32 v76, v0
	v_mov_b32_e32 v77, v0
	v_mov_b32_e32 v78, v0
	v_mov_b32_e32 v79, v0
	v_mov_b32_e32 v88, v0
	v_mov_b32_e32 v89, v0
	v_mov_b32_e32 v90, v0
	v_mov_b32_e32 v91, v0
	v_mov_b32_e32 v92, v0
	v_mov_b32_e32 v93, v0
	v_mov_b32_e32 v94, v0
	v_mov_b32_e32 v95, v0
	v_mov_b32_e32 v104, v0
	v_mov_b32_e32 v105, v0
	v_mov_b32_e32 v106, v0
	v_mov_b32_e32 v107, v0
	v_mov_b32_e32 v108, v0
	v_mov_b32_e32 v109, v0
	v_mov_b32_e32 v110, v0
	v_mov_b32_e32 v111, v0
	v_mov_b32_e32 v124, v0
	v_mov_b32_e32 v125, v0
	v_mov_b32_e32 v126, v0
	v_mov_b32_e32 v127, v0
	v_mov_b32_e32 v120, v0
	v_mov_b32_e32 v121, v0
	v_mov_b32_e32 v122, v0
	v_mov_b32_e32 v123, v0
	.p2align	6

; template <class Epi, class Sched, bool ALIGN_EPI = false, bool SP2 = false>
; __device__ __forceinline__ void gemm_phase(PG8_LAS unsigned char* lds, const Gemm g, const Sched& S, const Epi& E) {
;     ...
;         const bool has_next = S.next(ui + 1, nxt);
;         const char* nA = has_next ? (const char*)g.A + (size_t)nxt.pm * tstep : cA; const char* nB = has_next ? (const char*)g.Bt + (size_t)nxt.pn * tstep : cB;
;         for (int t = 0; t < nt; t += 2) {
;             const bool last = (t == nt - 2);
;             const char* a1 = cA + (size_t)(t + 1) * kstep;
;             const char* a2 = last ? nA : cA + (size_t)(t + 2) * kstep; const char* b2 = last ? nB : cB + (size_t)(t + 2) * kstep;
;             const char* a3 = a2 + kstep; const char* b3 = b2 + kstep;
;     ...
; #pragma unroll
;         for (int a = 0; a < 2; ++a)
; #pragma unroll
;             for (int b = 0; b < 2; ++b)
; #pragma unroll
;                 for (int m = 0; m < 4; ++m)
; #pragma unroll
;                     for (int n = 0; n < 2; ++n) acc[a][b][m][n] = (f32x4){0.f, 0.f, 0.f, 0.f};
;         cur = nxt; cA = nA; cB = nB; ++ui;
.LBB0_1167:
	s_and_b64 vcc, exec, s[6:7]
	s_cbranch_vccz .Lzs_9
	v_mov_b32_e32 v127, 0
	v_mov_b32_e32 v126, v127
	v_mov_b32_e32 v125, v127
	v_mov_b32_e32 v124, v127
	v_mov_b32_e32 v123, v127
	v_mov_b32_e32 v122, v127
	v_mov_b32_e32 v121, v127
	v_mov_b32_e32 v120, v127
	v_mov_b32_e32 v111, v127
	v_mov_b32_e32 v110, v127
	v_mov_b32_e32 v109, v127
	v_mov_b32_e32 v108, v127
	v_mov_b32_e32 v107, v127
	v_mov_b32_e32 v106, v127
	v_mov_b32_e32 v105, v127
	v_mov_b32_e32 v104, v127
	v_mov_b32_e32 v95, v127
	v_mov_b32_e32 v94, v127
	v_mov_b32_e32 v93, v127
	v_mov_b32_e32 v92, v127
	v_mov_b32_e32 v91, v127
	v_mov_b32_e32 v90, v127
	v_mov_b32_e32 v89, v127
	v_mov_b32_e32 v88, v127
	v_mov_b32_e32 v79, v127
	v_mov_b32_e32 v78, v127
	v_mov_b32_e32 v77, v127
	v_mov_b32_e32 v76, v127
	v_mov_b32_e32 v75, v127
	v_mov_b32_e32 v74, v127
	v_mov_b32_e32 v73, v127
	v_mov_b32_e32 v72, v127
	v_mov_b32_e32 v119, v127
	v_mov_b32_e32 v118, v127
	v_mov_b32_e32 v117, v127
	v_mov_b32_e32 v116, v127
	v_mov_b32_e32 v115, v127
	v_mov_b32_e32 v114, v127
	v_mov_b32_e32 v113, v127
	v_mov_b32_e32 v112, v127
	v_mov_b32_e32 v103, v127
	v_mov_b32_e32 v102, v127
	v_mov_b32_e32 v101, v127
	v_mov_b32_e32 v100, v127
	v_mov_b32_e32 v99, v127
	v_mov_b32_e32 v98, v127
	v_mov_b32_e32 v97, v127
	v_mov_b32_e32 v96, v127
	v_mov_b32_e32 v87, v127
	v_mov_b32_e32 v86, v127
	v_mov_b32_e32 v85, v127
	v_mov_b32_e32 v84, v127
	v_mov_b32_e32 v83, v127
	v_mov_b32_e32 v82, v127
	v_mov_b32_e32 v81, v127
	v_mov_b32_e32 v80, v127
	v_mov_b32_e32 v71, v127
	v_mov_b32_e32 v70, v127
	v_mov_b32_e32 v69, v127
	v_mov_b32_e32 v68, v127
	v_mov_b32_e32 v67, v127
	v_mov_b32_e32 v66, v127
	v_mov_b32_e32 v65, v127
	v_mov_b32_e32 v64, v127
	v_mov_b32_e32 v63, v127
	v_mov_b32_e32 v62, v127
	v_mov_b32_e32 v61, v127
	v_mov_b32_e32 v60, v127
	v_mov_b32_e32 v59, v127
	v_mov_b32_e32 v58, v127
	v_mov_b32_e32 v57, v127
	v_mov_b32_e32 v56, v127
	v_mov_b32_e32 v47, v127
	v_mov_b32_e32 v46, v127
	v_mov_b32_e32 v45, v127
	v_mov_b32_e32 v44, v127
	v_mov_b32_e32 v43, v127
	v_mov_b32_e32 v42, v127
	v_mov_b32_e32 v41, v127
	v_mov_b32_e32 v40, v127
	v_mov_b32_e32 v31, v127
	v_mov_b32_e32 v30, v127
	v_mov_b32_e32 v29, v127
	v_mov_b32_e32 v28, v127
	v_mov_b32_e32 v27, v127
	v_mov_b32_e32 v26, v127
	v_mov_b32_e32 v25, v127
	v_mov_b32_e32 v24, v127
	v_mov_b32_e32 v15, v127
	v_mov_b32_e32 v14, v127
	v_mov_b32_e32 v13, v127
	v_mov_b32_e32 v12, v127
	v_mov_b32_e32 v11, v127
	v_mov_b32_e32 v10, v127
	v_mov_b32_e32 v9, v127
	v_mov_b32_e32 v8, v127
	v_mov_b32_e32 v55, v127
	v_mov_b32_e32 v54, v127
	v_mov_b32_e32 v53, v127
	v_mov_b32_e32 v52, v127
	v_mov_b32_e32 v51, v127
	v_mov_b32_e32 v50, v127
	v_mov_b32_e32 v49, v127
	v_mov_b32_e32 v48, v127
	v_mov_b32_e32 v39, v127
	v_mov_b32_e32 v38, v127
	v_mov_b32_e32 v37, v127
	v_mov_b32_e32 v36, v127
	v_mov_b32_e32 v35, v127
	v_mov_b32_e32 v34, v127
	v_mov_b32_e32 v33, v127
	v_mov_b32_e32 v32, v127
	v_mov_b32_e32 v23, v127
	v_mov_b32_e32 v22, v127
	v_mov_b32_e32 v21, v127
	v_mov_b32_e32 v20, v127
	v_mov_b32_e32 v19, v127
	v_mov_b32_e32 v18, v127
	v_mov_b32_e32 v17, v127
	v_mov_b32_e32 v16, v127
	v_mov_b32_e32 v7, v127
	v_mov_b32_e32 v6, v127
	v_mov_b32_e32 v5, v127
	v_mov_b32_e32 v4, v127
	v_mov_b32_e32 v3, v127
	v_mov_b32_e32 v2, v127
	v_mov_b32_e32 v1, v127
	v_mov_b32_e32 v0, v127
	s_branch .LBB0_1170
.Lzs_9:
	v_mov_b32_e32 v0, 0
	v_lshl_add_u64 v[154:155], v[154:155], 0, s[28:29]
	v_lshl_add_u64 v[158:159], v[158:159], 0, s[24:25]
	s_mov_b32 s10, 0
	v_mov_b32_e32 v1, v0
	v_mov_b32_e32 v2, v0
	v_mov_b32_e32 v3, v0
	v_mov_b32_e32 v4, v0
	v_mov_b32_e32 v5, v0
	v_mov_b32_e32 v6, v0
	v_mov_b32_e32 v7, v0
	v_mov_b32_e32 v16, v0
	v_mov_b32_e32 v17, v0
	v_mov_b32_e32 v18, v0
	v_mov_b32_e32 v19, v0
	v_mov_b32_e32 v20, v0
	v_mov_b32_e32 v21, v0
	v_mov_b32_e32 v22, v0
	v_mov_b32_e32 v23, v0
	v_mov_b32_e32 v32, v0
	v_mov_b32_e32 v33, v0
	v_mov_b32_e32 v34, v0
	v_mov_b32_e32 v35, v0
	v_mov_b32_e32 v36, v0
	v_mov_b32_e32 v37, v0
	v_mov_b32_e32 v38, v0
	v_mov_b32_e32 v39, v0
	v_mov_b32_e32 v48, v0
	v_mov_b32_e32 v49, v0
	v_mov_b32_e32 v50, v0
	v_mov_b32_e32 v51, v0
	v_mov_b32_e32 v52, v0
	v_mov_b32_e32 v53, v0
	v_mov_b32_e32 v54, v0
	v_mov_b32_e32 v55, v0
	v_mov_b32_e32 v8, v0
	v_mov_b32_e32 v9, v0
	v_mov_b32_e32 v10, v0
	v_mov_b32_e32 v11, v0
	v_mov_b32_e32 v12, v0
	v_mov_b32_e32 v13, v0
	v_mov_b32_e32 v14, v0
	v_mov_b32_e32 v15, v0
	v_mov_b32_e32 v24, v0
	v_mov_b32_e32 v25, v0
	v_mov_b32_e32 v26, v0
	v_mov_b32_e32 v27, v0
	v_mov_b32_e32 v28, v0
	v_mov_b32_e32 v29, v0
	v_mov_b32_e32 v30, v0
	v_mov_b32_e32 v31, v0
	v_mov_b32_e32 v40, v0
	v_mov_b32_e32 v41, v0
	v_mov_b32_e32 v42, v0
	v_mov_b32_e32 v43, v0
	v_mov_b32_e32 v44, v0
	v_mov_b32_e32 v45, v0
	v_mov_b32_e32 v46, v0
	v_mov_b32_e32 v47, v0
	v_mov_b32_e32 v56, v0
	v_mov_b32_e32 v57, v0
	v_mov_b32_e32 v58, v0
	v_mov_b32_e32 v59, v0
	v_mov_b32_e32 v60, v0
	v_mov_b32_e32 v61, v0
	v_mov_b32_e32 v62, v0
	v_mov_b32_e32 v63, v0
	v_mov_b32_e32 v64, v0
	v_mov_b32_e32 v65, v0
	v_mov_b32_e32 v66, v0
	v_mov_b32_e32 v67, v0
	v_mov_b32_e32 v68, v0
	v_mov_b32_e32 v69, v0
	v_mov_b32_e32 v70, v0
	v_mov_b32_e32 v71, v0
	v_mov_b32_e32 v80, v0
	v_mov_b32_e32 v81, v0
	v_mov_b32_e32 v82, v0
	v_mov_b32_e32 v83, v0
	v_mov_b32_e32 v84, v0
	v_mov_b32_e32 v85, v0
	v_mov_b32_e32 v86, v0
	v_mov_b32_e32 v87, v0
	v_mov_b32_e32 v96, v0
	v_mov_b32_e32 v97, v0
	v_mov_b32_e32 v98, v0
	v_mov_b32_e32 v99, v0
	v_mov_b32_e32 v100, v0
	v_mov_b32_e32 v101, v0
	v_mov_b32_e32 v102, v0
	v_mov_b32_e32 v103, v0
	v_mov_b32_e32 v112, v0
	v_mov_b32_e32 v113, v0
	v_mov_b32_e32 v114, v0
	v_mov_b32_e32 v115, v0
	v_mov_b32_e32 v116, v0
	v_mov_b32_e32 v117, v0
	v_mov_b32_e32 v118, v0
	v_mov_b32_e32 v119, v0
	v_mov_b32_e32 v72, v0
	v_mov_b32_e32 v73, v0
	v_mov_b32_e32 v74, v0
	v_mov_b32_e32 v75, v0
	v_mov_b32_e32 v76, v0
	v_mov_b32_e32 v77, v0
	v_mov_b32_e32 v78, v0
	v_mov_b32_e32 v79, v0
	v_mov_b32_e32 v88, v0
	v_mov_b32_e32 v89, v0
	v_mov_b32_e32 v90, v0
	v_mov_b32_e32 v91, v0
	v_mov_b32_e32 v92, v0
	v_mov_b32_e32 v93, v0
	v_mov_b32_e32 v94, v0
	v_mov_b32_e32 v95, v0
	v_mov_b32_e32 v104, v0
	v_mov_b32_e32 v105, v0
	v_mov_b32_e32 v106, v0
	v_mov_b32_e32 v107, v0
	v_mov_b32_e32 v108, v0
	v_mov_b32_e32 v109, v0
	v_mov_b32_e32 v110, v0
	v_mov_b32_e32 v111, v0
	v_mov_b32_e32 v120, v0
	v_mov_b32_e32 v121, v0
	v_mov_b32_e32 v122, v0
	v_mov_b32_e32 v123, v0
	v_mov_b32_e32 v124, v0
	v_mov_b32_e32 v125, v0
	v_mov_b32_e32 v126, v0
	v_mov_b32_e32 v127, v0
	.p2align	6

; template <class Epi, class Sched, bool ALIGN_EPI = false, bool SP2 = false>
; __device__ __forceinline__ void gemm_phase(PG8_LAS unsigned char* lds, const Gemm g, const Sched& S, const Epi& E) {
;     ...
;         const bool has_next = S.next(ui + 1, nxt);
;         const char* nA = has_next ? (const char*)g.A + (size_t)nxt.pm * tstep : cA; const char* nB = has_next ? (const char*)g.Bt + (size_t)nxt.pn * tstep : cB;
;         for (int t = 0; t < nt; t += 2) {
;             const bool last = (t == nt - 2);
;             const char* a1 = cA + (size_t)(t + 1) * kstep;
;             const char* a2 = last ? nA : cA + (size_t)(t + 2) * kstep; const char* b2 = last ? nB : cB + (size_t)(t + 2) * kstep;
;             const char* a3 = a2 + kstep; const char* b3 = b2 + kstep;
;     ...
; #pragma unroll
;         for (int a = 0; a < 2; ++a)
; #pragma unroll
;             for (int b = 0; b < 2; ++b)
; #pragma unroll
;                 for (int m = 0; m < 4; ++m)
; #pragma unroll
;                     for (int n = 0; n < 2; ++n) acc[a][b][m][n] = (f32x4){0.f, 0.f, 0.f, 0.f};
;         cur = nxt; cA = nA; cB = nB; ++ui;
.LBB0_1190:
	s_andn2_b64 vcc, exec, s[22:23]
	s_waitcnt lgkmcnt(0)
	s_cbranch_vccz .Lzs_8
	v_mov_b32_e32 v133, 0
	v_mov_b32_e32 v132, v133
	v_mov_b32_e32 v131, v133
	v_mov_b32_e32 v130, v133
	v_mov_b32_e32 v129, v133
	v_mov_b32_e32 v128, v133
	v_mov_b32_e32 v127, v133
	v_mov_b32_e32 v126, v133
	v_mov_b32_e32 v117, v133
	v_mov_b32_e32 v116, v133
	v_mov_b32_e32 v115, v133
	v_mov_b32_e32 v114, v133
	v_mov_b32_e32 v113, v133
	v_mov_b32_e32 v112, v133
	v_mov_b32_e32 v111, v133
	v_mov_b32_e32 v110, v133
	v_mov_b32_e32 v101, v133
	v_mov_b32_e32 v100, v133
	v_mov_b32_e32 v99, v133
	v_mov_b32_e32 v98, v133
	v_mov_b32_e32 v97, v133
	v_mov_b32_e32 v96, v133
	v_mov_b32_e32 v95, v133
	v_mov_b32_e32 v94, v133
	v_mov_b32_e32 v85, v133
	v_mov_b32_e32 v84, v133
	v_mov_b32_e32 v83, v133
	v_mov_b32_e32 v82, v133
	v_mov_b32_e32 v81, v133
	v_mov_b32_e32 v80, v133
	v_mov_b32_e32 v79, v133
	v_mov_b32_e32 v78, v133
	v_mov_b32_e32 v125, v133
	v_mov_b32_e32 v124, v133
	v_mov_b32_e32 v123, v133
	v_mov_b32_e32 v122, v133
	v_mov_b32_e32 v121, v133
	v_mov_b32_e32 v120, v133
	v_mov_b32_e32 v119, v133
	v_mov_b32_e32 v118, v133
	v_mov_b32_e32 v109, v133
	v_mov_b32_e32 v108, v133
	v_mov_b32_e32 v107, v133
	v_mov_b32_e32 v106, v133
	v_mov_b32_e32 v105, v133
	v_mov_b32_e32 v104, v133
	v_mov_b32_e32 v103, v133
	v_mov_b32_e32 v102, v133
	v_mov_b32_e32 v93, v133
	v_mov_b32_e32 v92, v133
	v_mov_b32_e32 v91, v133
	v_mov_b32_e32 v90, v133
	v_mov_b32_e32 v89, v133
	v_mov_b32_e32 v88, v133
	v_mov_b32_e32 v87, v133
	v_mov_b32_e32 v86, v133
	v_mov_b32_e32 v77, v133
	v_mov_b32_e32 v76, v133
	v_mov_b32_e32 v75, v133
	v_mov_b32_e32 v74, v133
	v_mov_b32_e32 v73, v133
	v_mov_b32_e32 v72, v133
	v_mov_b32_e32 v71, v133
	v_mov_b32_e32 v70, v133
	v_mov_b32_e32 v69, v133
	v_mov_b32_e32 v68, v133
	v_mov_b32_e32 v67, v133
	v_mov_b32_e32 v66, v133
	v_mov_b32_e32 v65, v133
	v_mov_b32_e32 v64, v133
	v_mov_b32_e32 v63, v133
	v_mov_b32_e32 v62, v133
	v_mov_b32_e32 v53, v133
	v_mov_b32_e32 v52, v133
	v_mov_b32_e32 v51, v133
	v_mov_b32_e32 v50, v133
	v_mov_b32_e32 v49, v133
	v_mov_b32_e32 v48, v133
	v_mov_b32_e32 v47, v133
	v_mov_b32_e32 v46, v133
	v_mov_b32_e32 v37, v133
	v_mov_b32_e32 v36, v133
	v_mov_b32_e32 v35, v133
	v_mov_b32_e32 v34, v133
	v_mov_b32_e32 v33, v133
	v_mov_b32_e32 v32, v133
	v_mov_b32_e32 v31, v133
	v_mov_b32_e32 v30, v133
	v_mov_b32_e32 v21, v133
	v_mov_b32_e32 v20, v133
	v_mov_b32_e32 v19, v133
	v_mov_b32_e32 v18, v133
	v_mov_b32_e32 v17, v133
	v_mov_b32_e32 v16, v133
	v_mov_b32_e32 v15, v133
	v_mov_b32_e32 v14, v133
	v_mov_b32_e32 v61, v133
	v_mov_b32_e32 v60, v133
	v_mov_b32_e32 v59, v133
	v_mov_b32_e32 v58, v133
	v_mov_b32_e32 v57, v133
	v_mov_b32_e32 v56, v133
	v_mov_b32_e32 v55, v133
	v_mov_b32_e32 v54, v133
	v_mov_b32_e32 v45, v133
	v_mov_b32_e32 v44, v133
	v_mov_b32_e32 v43, v133
	v_mov_b32_e32 v42, v133
	v_mov_b32_e32 v41, v133
	v_mov_b32_e32 v40, v133
	v_mov_b32_e32 v39, v133
	v_mov_b32_e32 v38, v133
	v_mov_b32_e32 v29, v133
	v_mov_b32_e32 v28, v133
	v_mov_b32_e32 v27, v133
	v_mov_b32_e32 v26, v133
	v_mov_b32_e32 v25, v133
	v_mov_b32_e32 v24, v133
	v_mov_b32_e32 v23, v133
	v_mov_b32_e32 v22, v133
	v_mov_b32_e32 v13, v133
	v_mov_b32_e32 v12, v133
	v_mov_b32_e32 v11, v133
	v_mov_b32_e32 v10, v133
	v_mov_b32_e32 v9, v133
	v_mov_b32_e32 v8, v133
	v_mov_b32_e32 v7, v133
	v_mov_b32_e32 v6, v133
	s_branch .LBB0_1193
.Lzs_8:
	v_mov_b32_e32 v6, 0
	v_lshl_add_u64 v[134:135], v[134:135], 0, s[26:27]
	v_lshl_add_u64 v[136:137], v[136:137], 0, s[20:21]
	s_mov_b32 s10, 0
	v_mov_b32_e32 v7, v6
	v_mov_b32_e32 v8, v6
	v_mov_b32_e32 v9, v6
	v_mov_b32_e32 v10, v6
	v_mov_b32_e32 v11, v6
	v_mov_b32_e32 v12, v6
	v_mov_b32_e32 v13, v6
	v_mov_b32_e32 v22, v6
	v_mov_b32_e32 v23, v6
	v_mov_b32_e32 v24, v6
	v_mov_b32_e32 v25, v6
	v_mov_b32_e32 v26, v6
	v_mov_b32_e32 v27, v6
	v_mov_b32_e32 v28, v6
	v_mov_b32_e32 v29, v6
	v_mov_b32_e32 v38, v6
	v_mov_b32_e32 v39, v6
	v_mov_b32_e32 v40, v6
	v_mov_b32_e32 v41, v6
	v_mov_b32_e32 v42, v6
	v_mov_b32_e32 v43, v6
	v_mov_b32_e32 v44, v6
	v_mov_b32_e32 v45, v6
	v_mov_b32_e32 v54, v6
	v_mov_b32_e32 v55, v6
	v_mov_b32_e32 v56, v6
	v_mov_b32_e32 v57, v6
	v_mov_b32_e32 v58, v6
	v_mov_b32_e32 v59, v6
	v_mov_b32_e32 v60, v6
	v_mov_b32_e32 v61, v6
	v_mov_b32_e32 v14, v6
	v_mov_b32_e32 v15, v6
	v_mov_b32_e32 v16, v6
	v_mov_b32_e32 v17, v6
	v_mov_b32_e32 v18, v6
	v_mov_b32_e32 v19, v6
	v_mov_b32_e32 v20, v6
	v_mov_b32_e32 v21, v6
	v_mov_b32_e32 v30, v6
	v_mov_b32_e32 v31, v6
	v_mov_b32_e32 v32, v6
	v_mov_b32_e32 v33, v6
	v_mov_b32_e32 v34, v6
	v_mov_b32_e32 v35, v6
	v_mov_b32_e32 v36, v6
	v_mov_b32_e32 v37, v6
	v_mov_b32_e32 v46, v6
	v_mov_b32_e32 v47, v6
	v_mov_b32_e32 v48, v6
	v_mov_b32_e32 v49, v6
	v_mov_b32_e32 v50, v6
	v_mov_b32_e32 v51, v6
	v_mov_b32_e32 v52, v6
	v_mov_b32_e32 v53, v6
	v_mov_b32_e32 v62, v6
	v_mov_b32_e32 v63, v6
	v_mov_b32_e32 v64, v6
	v_mov_b32_e32 v65, v6
	v_mov_b32_e32 v66, v6
	v_mov_b32_e32 v67, v6
	v_mov_b32_e32 v68, v6
	v_mov_b32_e32 v69, v6
	v_mov_b32_e32 v70, v6
	v_mov_b32_e32 v71, v6
	v_mov_b32_e32 v72, v6
	v_mov_b32_e32 v73, v6
	v_mov_b32_e32 v74, v6
	v_mov_b32_e32 v75, v6
	v_mov_b32_e32 v76, v6
	v_mov_b32_e32 v77, v6
	v_mov_b32_e32 v86, v6
	v_mov_b32_e32 v87, v6
	v_mov_b32_e32 v88, v6
	v_mov_b32_e32 v89, v6
	v_mov_b32_e32 v90, v6
	v_mov_b32_e32 v91, v6
	v_mov_b32_e32 v92, v6
	v_mov_b32_e32 v93, v6
	v_mov_b32_e32 v102, v6
	v_mov_b32_e32 v103, v6
	v_mov_b32_e32 v104, v6
	v_mov_b32_e32 v105, v6
	v_mov_b32_e32 v106, v6
	v_mov_b32_e32 v107, v6
	v_mov_b32_e32 v108, v6
	v_mov_b32_e32 v109, v6
	v_mov_b32_e32 v118, v6
	v_mov_b32_e32 v119, v6
	v_mov_b32_e32 v120, v6
	v_mov_b32_e32 v121, v6
	v_mov_b32_e32 v122, v6
	v_mov_b32_e32 v123, v6
	v_mov_b32_e32 v124, v6
	v_mov_b32_e32 v125, v6
	v_mov_b32_e32 v78, v6
	v_mov_b32_e32 v79, v6
	v_mov_b32_e32 v80, v6
	v_mov_b32_e32 v81, v6
	v_mov_b32_e32 v82, v6
	v_mov_b32_e32 v83, v6
	v_mov_b32_e32 v84, v6
	v_mov_b32_e32 v85, v6
	v_mov_b32_e32 v94, v6
	v_mov_b32_e32 v95, v6
	v_mov_b32_e32 v96, v6
	v_mov_b32_e32 v97, v6
	v_mov_b32_e32 v98, v6
	v_mov_b32_e32 v99, v6
	v_mov_b32_e32 v100, v6
	v_mov_b32_e32 v101, v6
	v_mov_b32_e32 v110, v6
	v_mov_b32_e32 v111, v6
	v_mov_b32_e32 v112, v6
	v_mov_b32_e32 v113, v6
	v_mov_b32_e32 v114, v6
	v_mov_b32_e32 v115, v6
	v_mov_b32_e32 v116, v6
	v_mov_b32_e32 v117, v6
	v_mov_b32_e32 v126, v6
	v_mov_b32_e32 v127, v6
	v_mov_b32_e32 v128, v6
	v_mov_b32_e32 v129, v6
	v_mov_b32_e32 v130, v6
	v_mov_b32_e32 v131, v6
	v_mov_b32_e32 v132, v6
	v_mov_b32_e32 v133, v6
	.p2align	6

; template <class Epi, class Sched, bool ALIGN_EPI = false, bool SP2 = false>
; __device__ __forceinline__ void gemm_phase(PG8_LAS unsigned char* lds, const Gemm g, const Sched& S, const Epi& E) {
;     ...
;         const bool has_next = S.next(ui + 1, nxt);
;         const char* nA = has_next ? (const char*)g.A + (size_t)nxt.pm * tstep : cA; const char* nB = has_next ? (const char*)g.Bt + (size_t)nxt.pn * tstep : cB;
;         for (int t = 0; t < nt; t += 2) {
;             const bool last = (t == nt - 2);
;             const char* a1 = cA + (size_t)(t + 1) * kstep;
;             const char* a2 = last ? nA : cA + (size_t)(t + 2) * kstep; const char* b2 = last ? nB : cB + (size_t)(t + 2) * kstep;
;             const char* a3 = a2 + kstep; const char* b3 = b2 + kstep;
;     ...
; #pragma unroll
;         for (int a = 0; a < 2; ++a)
; #pragma unroll
;             for (int b = 0; b < 2; ++b)
; #pragma unroll
;                 for (int m = 0; m < 4; ++m)
; #pragma unroll
;                     for (int n = 0; n < 2; ++n) acc[a][b][m][n] = (f32x4){0.f, 0.f, 0.f, 0.f};
;         cur = nxt; cA = nA; cB = nB; ++ui;
.LBB0_1421:
	s_andn2_b64 vcc, exec, s[28:29]
	s_cbranch_vccz .Lzs_5
	v_mov_b32_e32 v127, 0
	v_mov_b32_e32 v126, v127
	v_mov_b32_e32 v125, v127
	v_mov_b32_e32 v124, v127
	v_mov_b32_e32 v123, v127
	v_mov_b32_e32 v122, v127
	v_mov_b32_e32 v121, v127
	v_mov_b32_e32 v120, v127
	v_mov_b32_e32 v111, v127
	v_mov_b32_e32 v110, v127
	v_mov_b32_e32 v109, v127
	v_mov_b32_e32 v108, v127
	v_mov_b32_e32 v107, v127
	v_mov_b32_e32 v106, v127
	v_mov_b32_e32 v105, v127
	v_mov_b32_e32 v104, v127
	v_mov_b32_e32 v95, v127
	v_mov_b32_e32 v94, v127
	v_mov_b32_e32 v93, v127
	v_mov_b32_e32 v92, v127
	v_mov_b32_e32 v91, v127
	v_mov_b32_e32 v90, v127
	v_mov_b32_e32 v89, v127
	v_mov_b32_e32 v88, v127
	v_mov_b32_e32 v79, v127
	v_mov_b32_e32 v78, v127
	v_mov_b32_e32 v77, v127
	v_mov_b32_e32 v76, v127
	v_mov_b32_e32 v75, v127
	v_mov_b32_e32 v74, v127
	v_mov_b32_e32 v73, v127
	v_mov_b32_e32 v72, v127
	v_mov_b32_e32 v119, v127
	v_mov_b32_e32 v118, v127
	v_mov_b32_e32 v117, v127
	v_mov_b32_e32 v116, v127
	v_mov_b32_e32 v115, v127
	v_mov_b32_e32 v114, v127
	v_mov_b32_e32 v113, v127
	v_mov_b32_e32 v112, v127
	v_mov_b32_e32 v103, v127
	v_mov_b32_e32 v102, v127
	v_mov_b32_e32 v101, v127
	v_mov_b32_e32 v100, v127
	v_mov_b32_e32 v99, v127
	v_mov_b32_e32 v98, v127
	v_mov_b32_e32 v97, v127
	v_mov_b32_e32 v96, v127
	v_mov_b32_e32 v87, v127
	v_mov_b32_e32 v86, v127
	v_mov_b32_e32 v85, v127
	v_mov_b32_e32 v84, v127
	v_mov_b32_e32 v83, v127
	v_mov_b32_e32 v82, v127
	v_mov_b32_e32 v81, v127
	v_mov_b32_e32 v80, v127
	v_mov_b32_e32 v71, v127
	v_mov_b32_e32 v70, v127
	v_mov_b32_e32 v69, v127
	v_mov_b32_e32 v68, v127
	v_mov_b32_e32 v67, v127
	v_mov_b32_e32 v66, v127
	v_mov_b32_e32 v65, v127
	v_mov_b32_e32 v64, v127
	v_mov_b32_e32 v63, v127
	v_mov_b32_e32 v62, v127
	v_mov_b32_e32 v61, v127
	v_mov_b32_e32 v60, v127
	v_mov_b32_e32 v59, v127
	v_mov_b32_e32 v58, v127
	v_mov_b32_e32 v57, v127
	v_mov_b32_e32 v56, v127
	v_mov_b32_e32 v47, v127
	v_mov_b32_e32 v46, v127
	v_mov_b32_e32 v45, v127
	v_mov_b32_e32 v44, v127
	v_mov_b32_e32 v43, v127
	v_mov_b32_e32 v42, v127
	v_mov_b32_e32 v41, v127
	v_mov_b32_e32 v40, v127
	v_mov_b32_e32 v31, v127
	v_mov_b32_e32 v30, v127
	v_mov_b32_e32 v29, v127
	v_mov_b32_e32 v28, v127
	v_mov_b32_e32 v27, v127
	v_mov_b32_e32 v26, v127
	v_mov_b32_e32 v25, v127
	v_mov_b32_e32 v24, v127
	v_mov_b32_e32 v15, v127
	v_mov_b32_e32 v14, v127
	v_mov_b32_e32 v13, v127
	v_mov_b32_e32 v12, v127
	v_mov_b32_e32 v11, v127
	v_mov_b32_e32 v10, v127
	v_mov_b32_e32 v9, v127
	v_mov_b32_e32 v8, v127
	v_mov_b32_e32 v55, v127
	v_mov_b32_e32 v54, v127
	v_mov_b32_e32 v53, v127
	v_mov_b32_e32 v52, v127
	v_mov_b32_e32 v51, v127
	v_mov_b32_e32 v50, v127
	v_mov_b32_e32 v49, v127
	v_mov_b32_e32 v48, v127
	v_mov_b32_e32 v39, v127
	v_mov_b32_e32 v38, v127
	v_mov_b32_e32 v37, v127
	v_mov_b32_e32 v36, v127
	v_mov_b32_e32 v35, v127
	v_mov_b32_e32 v34, v127
	v_mov_b32_e32 v33, v127
	v_mov_b32_e32 v32, v127
	v_mov_b32_e32 v23, v127
	v_mov_b32_e32 v22, v127
	v_mov_b32_e32 v21, v127
	v_mov_b32_e32 v20, v127
	v_mov_b32_e32 v19, v127
	v_mov_b32_e32 v18, v127
	v_mov_b32_e32 v17, v127
	v_mov_b32_e32 v16, v127
	v_mov_b32_e32 v7, v127
	v_mov_b32_e32 v6, v127
	v_mov_b32_e32 v5, v127
	v_mov_b32_e32 v4, v127
	v_mov_b32_e32 v3, v127
	v_mov_b32_e32 v2, v127
	v_mov_b32_e32 v1, v127
	v_mov_b32_e32 v0, v127
	s_branch .LBB0_1424
.Lzs_5:
	v_mov_b32_e32 v0, 0
	v_lshl_add_u64 v[128:129], v[128:129], 0, s[36:37]
	v_lshl_add_u64 v[130:131], v[130:131], 0, s[26:27]
	s_mov_b32 s10, 0
	v_mov_b32_e32 v1, v0
	v_mov_b32_e32 v2, v0
	v_mov_b32_e32 v3, v0
	v_mov_b32_e32 v4, v0
	v_mov_b32_e32 v5, v0
	v_mov_b32_e32 v6, v0
	v_mov_b32_e32 v7, v0
	v_mov_b32_e32 v16, v0
	v_mov_b32_e32 v17, v0
	v_mov_b32_e32 v18, v0
	v_mov_b32_e32 v19, v0
	v_mov_b32_e32 v20, v0
	v_mov_b32_e32 v21, v0
	v_mov_b32_e32 v22, v0
	v_mov_b32_e32 v23, v0
	v_mov_b32_e32 v32, v0
	v_mov_b32_e32 v33, v0
	v_mov_b32_e32 v34, v0
	v_mov_b32_e32 v35, v0
	v_mov_b32_e32 v36, v0
	v_mov_b32_e32 v37, v0
	v_mov_b32_e32 v38, v0
	v_mov_b32_e32 v39, v0
	v_mov_b32_e32 v48, v0
	v_mov_b32_e32 v49, v0
	v_mov_b32_e32 v50, v0
	v_mov_b32_e32 v51, v0
	v_mov_b32_e32 v52, v0
	v_mov_b32_e32 v53, v0
	v_mov_b32_e32 v54, v0
	v_mov_b32_e32 v55, v0
	v_mov_b32_e32 v8, v0
	v_mov_b32_e32 v9, v0
	v_mov_b32_e32 v10, v0
	v_mov_b32_e32 v11, v0
	v_mov_b32_e32 v12, v0
	v_mov_b32_e32 v13, v0
	v_mov_b32_e32 v14, v0
	v_mov_b32_e32 v15, v0
	v_mov_b32_e32 v24, v0
	v_mov_b32_e32 v25, v0
	v_mov_b32_e32 v26, v0
	v_mov_b32_e32 v27, v0
	v_mov_b32_e32 v28, v0
	v_mov_b32_e32 v29, v0
	v_mov_b32_e32 v30, v0
	v_mov_b32_e32 v31, v0
	v_mov_b32_e32 v40, v0
	v_mov_b32_e32 v41, v0
	v_mov_b32_e32 v42, v0
	v_mov_b32_e32 v43, v0
	v_mov_b32_e32 v44, v0
	v_mov_b32_e32 v45, v0
	v_mov_b32_e32 v46, v0
	v_mov_b32_e32 v47, v0
	v_mov_b32_e32 v56, v0
	v_mov_b32_e32 v57, v0
	v_mov_b32_e32 v58, v0
	v_mov_b32_e32 v59, v0
	v_mov_b32_e32 v60, v0
	v_mov_b32_e32 v61, v0
	v_mov_b32_e32 v62, v0
	v_mov_b32_e32 v63, v0
	v_mov_b32_e32 v64, v0
	v_mov_b32_e32 v65, v0
	v_mov_b32_e32 v66, v0
	v_mov_b32_e32 v67, v0
	v_mov_b32_e32 v68, v0
	v_mov_b32_e32 v69, v0
	v_mov_b32_e32 v70, v0
	v_mov_b32_e32 v71, v0
	v_mov_b32_e32 v80, v0
	v_mov_b32_e32 v81, v0
	v_mov_b32_e32 v82, v0
	v_mov_b32_e32 v83, v0
	v_mov_b32_e32 v84, v0
	v_mov_b32_e32 v85, v0
	v_mov_b32_e32 v86, v0
	v_mov_b32_e32 v87, v0
	v_mov_b32_e32 v96, v0
	v_mov_b32_e32 v97, v0
	v_mov_b32_e32 v98, v0
	v_mov_b32_e32 v99, v0
	v_mov_b32_e32 v100, v0
	v_mov_b32_e32 v101, v0
	v_mov_b32_e32 v102, v0
	v_mov_b32_e32 v103, v0
	v_mov_b32_e32 v112, v0
	v_mov_b32_e32 v113, v0
	v_mov_b32_e32 v114, v0
	v_mov_b32_e32 v115, v0
	v_mov_b32_e32 v116, v0
	v_mov_b32_e32 v117, v0
	v_mov_b32_e32 v118, v0
	v_mov_b32_e32 v119, v0
	v_mov_b32_e32 v72, v0
	v_mov_b32_e32 v73, v0
	v_mov_b32_e32 v74, v0
	v_mov_b32_e32 v75, v0
	v_mov_b32_e32 v76, v0
	v_mov_b32_e32 v77, v0
	v_mov_b32_e32 v78, v0
	v_mov_b32_e32 v79, v0
	v_mov_b32_e32 v88, v0
	v_mov_b32_e32 v89, v0
	v_mov_b32_e32 v90, v0
	v_mov_b32_e32 v91, v0
	v_mov_b32_e32 v92, v0
	v_mov_b32_e32 v93, v0
	v_mov_b32_e32 v94, v0
	v_mov_b32_e32 v95, v0
	v_mov_b32_e32 v104, v0
	v_mov_b32_e32 v105, v0
	v_mov_b32_e32 v106, v0
	v_mov_b32_e32 v107, v0
	v_mov_b32_e32 v108, v0
	v_mov_b32_e32 v109, v0
	v_mov_b32_e32 v110, v0
	v_mov_b32_e32 v111, v0
	v_mov_b32_e32 v120, v0
	v_mov_b32_e32 v121, v0
	v_mov_b32_e32 v122, v0
	v_mov_b32_e32 v123, v0
	v_mov_b32_e32 v124, v0
	v_mov_b32_e32 v125, v0
	v_mov_b32_e32 v126, v0
	v_mov_b32_e32 v127, v0
	.p2align	6
